# code placement: s_nop padding in load segments so all 24 K-loop MFMA blocks start at 4 mod 8 bytes
# speedup vs baseline: 1.0309x; 1.0025x over previous
; #define PG8_STAGE(bufoff, gbase, voff) do { _Pragma("unroll") for (int _i = 0; _i < 2; ++_i) \
;         __builtin_amdgcn_global_load_lds((const unsigned*)((const char*)(gbase) + (voff)[_i]), (PG8_LAS unsigned*)(lds + (bufoff) + ldsw + _i * 8192), 16, 0, 0); } while (0)
; #define PG8_LDA(dst, b, h) do { _Pragma("unroll") for (int m = 0; m < 4; ++m) _Pragma("unroll") for (int k = 0; k < 2; ++k) dst[m][k] = *(const PG8_LAS bf16x8*)(lds + PG8_SA(b, h) + aoff + m * 2048 + k * 1024); } while (0)
; #define PG8_LDB(dst, b, h) do { _Pragma("unroll") for (int n = 0; n < 2; ++n) _Pragma("unroll") for (int k = 0; k < 2; ++k) dst[n][k] = *(const PG8_LAS bf16x8*)(lds + PG8_SB(b, h) + boff + n * 2048 + k * 1024); } while (0)
; #define PG8_MMA(ai, bj, At, Bt) do { __builtin_amdgcn_s_setprio(1); _Pragma("unroll") for (int m = 0; m < 4; ++m) _Pragma("unroll") for (int n = 0; n < 2; ++n) _Pragma("unroll") for (int k = 0; k < 2; ++k) \
;         acc[ai][bj][m][n] = __builtin_amdgcn_mfma_f32_16x16x32_bf16(Bt[n][k], At[m][k], acc[ai][bj][m][n], 0, 0, 0); __builtin_amdgcn_s_setprio(0); } while (0)
; #define PG8_WAIT_V(n) asm volatile("s_waitcnt vmcnt(" #n ")" ::: "memory")
; #define PG8_WAIT_L(n) asm volatile("s_waitcnt lgkmcnt(" #n ")" ::: "memory")
; template <class Epi, class Sched, bool ALIGN_EPI = false, bool SP2 = false>
; __device__ __forceinline__ void gemm_phase(PG8_LAS unsigned char* lds, const Gemm g, const Sched& S, const Epi& E) {
;     ...
;             const bool last = (t == nt - 2);
;             const char* a1 = cA + (size_t)(t + 1) * kstep;
;             const char* a2 = last ? nA : cA + (size_t)(t + 2) * kstep; const char* b2 = last ? nB : cB + (size_t)(t + 2) * kstep;
;             const char* a3 = a2 + kstep; const char* b3 = b2 + kstep;
;             if (last && has_next) S.a_ready(nxt);
;             if constexpr (SP2) {
;             PG8_LDB(B0, 0, 0); PG8_LDB(B1, 0, 1); PG8_SCHED; PG8_LDA(At, 0, 0); PG8_STAGE(PG8_SA(1, 1), a1 + hstep, voffA);
;             PG8_WAIT_V(8); PG8_WAIT_L(0); PG8_BAR; PG8_MMA(0, 0, At, B0); PG8_MMA(0, 1, At, B1); PG8_BAR; PG8_SCHED;
;             PG8_LDA(At, 0, 1); PG8_STAGE(PG8_SB(0, 0), b2, voffB); PG8_STAGE(PG8_SB(0, 1), b2 + hstep, voffB); PG8_STAGE(PG8_SA(0, 0), a2, voffA);
;             PG8_WAIT_V(8); PG8_WAIT_L(0); PG8_BAR; PG8_MMA(1, 0, At, B0); PG8_MMA(1, 1, At, B1); PG8_BAR; PG8_SCHED;
.LBB0_36:
	s_add_u32 s18, s58, 0xffe00080
	s_addc_u32 s19, s59, -1
	s_add_i32 s47, 0, 0x10000
	s_cmpk_eq_i32 s46, 0x7c
	s_cselect_b32 s63, s45, s19
	s_cselect_b32 s62, s73, s18
	v_add_u32_e32 v160, s47, v143
	s_cselect_b32 s19, s37, s79
	s_cselect_b32 s18, s84, s78
	s_add_i32 s80, 0, 0x14000
	ds_read_b128 v[156:159], v160
	ds_read_b128 v[164:167], v160 offset:1024
	ds_read_b128 v[168:171], v160 offset:2048
	ds_read_b128 v[172:175], v160 offset:3072
	v_add_u32_e32 v160, s80, v143
	ds_read_b128 v[176:179], v160
	ds_read_b128 v[180:183], v160 offset:1024
	ds_read_b128 v[184:187], v160 offset:2048
	ds_read_b128 v[204:207], v160 offset:3072
	v_lshl_add_u64 v[160:161], s[58:59], 0, v[152:153]
	s_add_i32 m0, s5, 0xc000
	ds_read_b128 v[208:211], v163
	ds_read_b128 v[212:215], v163 offset:1024
	ds_read_b128 v[216:219], v163 offset:2048
	ds_read_b128 v[220:223], v163 offset:3072
	ds_read_b128 v[224:227], v163 offset:4096
	ds_read_b128 v[228:231], v163 offset:5120
	ds_read_b128 v[232:235], v163 offset:6144
	ds_read_b128 v[236:239], v163 offset:7168
	global_load_lds_dwordx4 v[160:161], off
	v_lshl_add_u64 v[160:161], s[58:59], 0, v[154:155]
	s_add_i32 m0, s5, 0xe000
	s_nop 0
	global_load_lds_dwordx4 v[160:161], off
	s_nop 0
	s_waitcnt vmcnt(8)
	s_waitcnt lgkmcnt(0)
	s_barrier
	s_setprio 1
	v_mfma_f32_16x16x32_bf16 v[126:129], v[156:159], v[208:211], v[126:129]
	v_mfma_f32_16x16x32_bf16 v[122:125], v[168:171], v[208:211], v[122:125]
	v_mfma_f32_16x16x32_bf16 v[110:113], v[156:159], v[216:219], v[110:113]
	v_mfma_f32_16x16x32_bf16 v[106:109], v[168:171], v[216:219], v[106:109]
	v_mfma_f32_16x16x32_bf16 v[94:97], v[156:159], v[224:227], v[94:97]
	v_mfma_f32_16x16x32_bf16 v[90:93], v[168:171], v[224:227], v[90:93]
	v_mfma_f32_16x16x32_bf16 v[78:81], v[156:159], v[232:235], v[78:81]
	v_mfma_f32_16x16x32_bf16 v[74:77], v[168:171], v[232:235], v[74:77]
	s_setprio 0
	s_setprio 1
	v_mfma_f32_16x16x32_bf16 v[126:129], v[164:167], v[212:215], v[126:129]
	v_mfma_f32_16x16x32_bf16 v[122:125], v[172:175], v[212:215], v[122:125]
	v_mfma_f32_16x16x32_bf16 v[110:113], v[164:167], v[220:223], v[110:113]
	v_mfma_f32_16x16x32_bf16 v[106:109], v[172:175], v[220:223], v[106:109]
	v_mfma_f32_16x16x32_bf16 v[94:97], v[164:167], v[228:231], v[94:97]
	v_mfma_f32_16x16x32_bf16 v[90:93], v[172:175], v[228:231], v[90:93]
	v_mfma_f32_16x16x32_bf16 v[78:81], v[164:167], v[236:239], v[78:81]
	v_mfma_f32_16x16x32_bf16 v[74:77], v[172:175], v[236:239], v[74:77]
	s_setprio 0
	s_setprio 1
	v_mfma_f32_16x16x32_bf16 v[118:121], v[176:179], v[208:211], v[118:121]
	v_mfma_f32_16x16x32_bf16 v[114:117], v[184:187], v[208:211], v[114:117]
	v_mfma_f32_16x16x32_bf16 v[102:105], v[176:179], v[216:219], v[102:105]
	v_mfma_f32_16x16x32_bf16 v[98:101], v[184:187], v[216:219], v[98:101]
	v_mfma_f32_16x16x32_bf16 v[86:89], v[176:179], v[224:227], v[86:89]
	v_mfma_f32_16x16x32_bf16 v[82:85], v[184:187], v[224:227], v[82:85]
	v_mfma_f32_16x16x32_bf16 v[70:73], v[176:179], v[232:235], v[70:73]
	v_mfma_f32_16x16x32_bf16 v[66:69], v[184:187], v[232:235], v[66:69]
	s_setprio 0
	s_setprio 1
	v_mfma_f32_16x16x32_bf16 v[118:121], v[180:183], v[212:215], v[118:121]
	v_mfma_f32_16x16x32_bf16 v[114:117], v[204:207], v[212:215], v[114:117]
	v_mfma_f32_16x16x32_bf16 v[102:105], v[180:183], v[220:223], v[102:105]
	v_mfma_f32_16x16x32_bf16 v[98:101], v[204:207], v[220:223], v[98:101]
	v_mfma_f32_16x16x32_bf16 v[86:89], v[180:183], v[228:231], v[86:89]
	v_mfma_f32_16x16x32_bf16 v[82:85], v[204:207], v[228:231], v[82:85]
	v_mfma_f32_16x16x32_bf16 v[70:73], v[180:183], v[236:239], v[70:73]
	v_mfma_f32_16x16x32_bf16 v[66:69], v[204:207], v[236:239], v[66:69]
	s_setprio 0
	s_barrier
	s_add_i32 s47, s47, s4
	v_lshl_add_u64 v[160:161], s[18:19], 0, v[148:149]
	s_mov_b32 m0, s47
	ds_read_b128 v[208:211], v163 offset:16384
	ds_read_b128 v[212:215], v163 offset:17408
	ds_read_b128 v[216:219], v163 offset:18432
	ds_read_b128 v[220:223], v163 offset:19456
	ds_read_b128 v[224:227], v163 offset:20480
	ds_read_b128 v[228:231], v163 offset:21504
	ds_read_b128 v[232:235], v163 offset:22528
	ds_read_b128 v[236:239], v163 offset:23552
	global_load_lds_dwordx4 v[160:161], off
	s_add_i32 m0, s47, 0x2000
	s_add_u32 s76, s18, 0x200000
	v_lshl_add_u64 v[240:241], s[18:19], 0, v[144:145]
	s_addc_u32 s77, s19, 0
	s_add_i32 s47, s80, s4
	global_load_lds_dwordx4 v[240:241], off
	v_lshl_add_u64 v[242:243], s[76:77], 0, v[148:149]
	s_mov_b32 m0, s47
	v_lshl_add_u64 v[244:245], s[62:63], 0, v[146:147]
	global_load_lds_dwordx4 v[242:243], off
	v_lshl_add_u64 v[242:243], s[76:77], 0, v[144:145]
	s_add_i32 m0, s47, 0x2000
	s_nop 0
	global_load_lds_dwordx4 v[242:243], off
	v_lshl_add_u64 v[242:243], s[62:63], 0, v[150:151]
	s_mov_b32 m0, s5
	s_nop 0
	global_load_lds_dwordx4 v[242:243], off
	s_mov_b32 m0, s30
	s_nop 0
	global_load_lds_dwordx4 v[244:245], off
	s_waitcnt vmcnt(8)
	s_waitcnt lgkmcnt(0)
	s_barrier
; #define PG8_STAGE(bufoff, gbase, voff) do { _Pragma("unroll") for (int _i = 0; _i < 2; ++_i) \
;         __builtin_amdgcn_global_load_lds((const unsigned*)((const char*)(gbase) + (voff)[_i]), (PG8_LAS unsigned*)(lds + (bufoff) + ldsw + _i * 8192), 16, 0, 0); } while (0)
; #define PG8_LDA(dst, b, h) do { _Pragma("unroll") for (int m = 0; m < 4; ++m) _Pragma("unroll") for (int k = 0; k < 2; ++k) dst[m][k] = *(const PG8_LAS bf16x8*)(lds + PG8_SA(b, h) + aoff + m * 2048 + k * 1024); } while (0)
; #define PG8_LDB(dst, b, h) do { _Pragma("unroll") for (int n = 0; n < 2; ++n) _Pragma("unroll") for (int k = 0; k < 2; ++k) dst[n][k] = *(const PG8_LAS bf16x8*)(lds + PG8_SB(b, h) + boff + n * 2048 + k * 1024); } while (0)
; #define PG8_MMA(ai, bj, At, Bt) do { __builtin_amdgcn_s_setprio(1); _Pragma("unroll") for (int m = 0; m < 4; ++m) _Pragma("unroll") for (int n = 0; n < 2; ++n) _Pragma("unroll") for (int k = 0; k < 2; ++k) \
;         acc[ai][bj][m][n] = __builtin_amdgcn_mfma_f32_16x16x32_bf16(Bt[n][k], At[m][k], acc[ai][bj][m][n], 0, 0, 0); __builtin_amdgcn_s_setprio(0); } while (0)
; #define PG8_WAIT_V(n) asm volatile("s_waitcnt vmcnt(" #n ")" ::: "memory")
; #define PG8_WAIT_L(n) asm volatile("s_waitcnt lgkmcnt(" #n ")" ::: "memory")
; #define PG8_BAR __builtin_amdgcn_s_barrier()
; #define PG8_SCHED __builtin_amdgcn_sched_barrier(0)
; template <class Epi, class Sched, bool ALIGN_EPI = false, bool SP2 = false>
; __device__ __forceinline__ void gemm_phase(PG8_LAS unsigned char* lds, const Gemm g, const Sched& S, const Epi& E) {
;     ...
;             PG8_WAIT_V(8); PG8_WAIT_L(0); PG8_BAR; PG8_MMA(1, 0, At, B0); PG8_MMA(1, 1, At, B1); PG8_BAR; PG8_SCHED;
;             PG8_LDB(B0, 1, 0); PG8_LDB(B1, 1, 1); PG8_SCHED; PG8_LDA(At, 1, 0); PG8_STAGE(PG8_SA(0, 1), a2 + hstep, voffA);
;             PG8_WAIT_V(8); PG8_WAIT_L(0); PG8_BAR; PG8_MMA(0, 0, At, B0); PG8_MMA(0, 1, At, B1); PG8_BAR; PG8_SCHED;
;             PG8_LDA(At, 1, 1); PG8_STAGE(PG8_SB(1, 0), b3, voffB); PG8_STAGE(PG8_SB(1, 1), b3 + hstep, voffB); PG8_STAGE(PG8_SA(1, 0), a3, voffA);
;             PG8_WAIT_V(8); PG8_WAIT_L(0); PG8_BAR; PG8_MMA(1, 0, At, B0); PG8_MMA(1, 1, At, B1); PG8_BAR; PG8_SCHED;
	s_setprio 1
	v_mfma_f32_16x16x32_bf16 v[62:65], v[156:159], v[208:211], v[62:65]
	v_mfma_f32_16x16x32_bf16 v[58:61], v[168:171], v[208:211], v[58:61]
	v_mfma_f32_16x16x32_bf16 v[46:49], v[156:159], v[216:219], v[46:49]
	v_mfma_f32_16x16x32_bf16 v[42:45], v[168:171], v[216:219], v[42:45]
	v_mfma_f32_16x16x32_bf16 v[30:33], v[156:159], v[224:227], v[30:33]
	v_mfma_f32_16x16x32_bf16 v[26:29], v[168:171], v[224:227], v[26:29]
	v_mfma_f32_16x16x32_bf16 v[14:17], v[156:159], v[232:235], v[14:17]
	v_mfma_f32_16x16x32_bf16 v[10:13], v[168:171], v[232:235], v[10:13]
	s_setprio 0
	s_setprio 1
	v_mfma_f32_16x16x32_bf16 v[62:65], v[164:167], v[212:215], v[62:65]
	v_mfma_f32_16x16x32_bf16 v[58:61], v[172:175], v[212:215], v[58:61]
	v_mfma_f32_16x16x32_bf16 v[46:49], v[164:167], v[220:223], v[46:49]
	v_mfma_f32_16x16x32_bf16 v[42:45], v[172:175], v[220:223], v[42:45]
	v_mfma_f32_16x16x32_bf16 v[30:33], v[164:167], v[228:231], v[30:33]
	v_mfma_f32_16x16x32_bf16 v[26:29], v[172:175], v[228:231], v[26:29]
	v_mfma_f32_16x16x32_bf16 v[14:17], v[164:167], v[236:239], v[14:17]
	v_mfma_f32_16x16x32_bf16 v[10:13], v[172:175], v[236:239], v[10:13]
	s_setprio 0
	s_setprio 1
	v_mfma_f32_16x16x32_bf16 v[54:57], v[176:179], v[208:211], v[54:57]
	v_mfma_f32_16x16x32_bf16 v[50:53], v[184:187], v[208:211], v[50:53]
	v_mfma_f32_16x16x32_bf16 v[38:41], v[176:179], v[216:219], v[38:41]
	v_mfma_f32_16x16x32_bf16 v[34:37], v[184:187], v[216:219], v[34:37]
	v_mfma_f32_16x16x32_bf16 v[22:25], v[176:179], v[224:227], v[22:25]
	v_mfma_f32_16x16x32_bf16 v[18:21], v[184:187], v[224:227], v[18:21]
	v_mfma_f32_16x16x32_bf16 v[6:9], v[176:179], v[232:235], v[6:9]
	v_mfma_f32_16x16x32_bf16 v[2:5], v[184:187], v[232:235], v[2:5]
	s_setprio 0
	s_setprio 1
	v_mfma_f32_16x16x32_bf16 v[54:57], v[180:183], v[212:215], v[54:57]
	v_mfma_f32_16x16x32_bf16 v[50:53], v[204:207], v[212:215], v[50:53]
	v_mfma_f32_16x16x32_bf16 v[38:41], v[180:183], v[220:223], v[38:41]
	v_mfma_f32_16x16x32_bf16 v[34:37], v[204:207], v[220:223], v[34:37]
	v_mfma_f32_16x16x32_bf16 v[22:25], v[180:183], v[228:231], v[22:25]
	v_mfma_f32_16x16x32_bf16 v[18:21], v[204:207], v[228:231], v[18:21]
	v_mfma_f32_16x16x32_bf16 v[6:9], v[180:183], v[236:239], v[6:9]
	v_mfma_f32_16x16x32_bf16 v[2:5], v[204:207], v[236:239], v[2:5]
	s_setprio 0
	s_barrier
	s_add_i32 s47, 0, 0x18000
	s_add_i32 s76, 0, 0x1c000
	v_add_u32_e32 v172, s47, v143
	v_add_u32_e32 v203, s76, v143
	ds_read_b128 v[156:159], v172
	ds_read_b128 v[164:167], v172 offset:1024
	ds_read_b128 v[168:171], v172 offset:2048
	ds_read_b128 v[172:175], v172 offset:3072
	ds_read_b128 v[176:179], v203
	ds_read_b128 v[180:183], v203 offset:1024
	ds_read_b128 v[184:187], v203 offset:2048
	ds_read_b128 v[204:207], v203 offset:3072
	s_add_u32 s62, s62, 0x200000
	s_addc_u32 s63, s63, 0
	s_mov_b32 m0, s57
	v_lshl_add_u64 v[246:247], s[62:63], 0, v[150:151]
	ds_read_b128 v[208:211], v163 offset:32768
	ds_read_b128 v[212:215], v163 offset:33792
	ds_read_b128 v[216:219], v163 offset:34816
	ds_read_b128 v[220:223], v163 offset:35840
	ds_read_b128 v[224:227], v163 offset:36864
	ds_read_b128 v[228:231], v163 offset:37888
	ds_read_b128 v[232:235], v163 offset:38912
	ds_read_b128 v[236:239], v163 offset:39936
	global_load_lds_dwordx4 v[246:247], off
	v_lshl_add_u64 v[246:247], s[62:63], 0, v[146:147]
	s_mov_b32 m0, s67
	s_nop 0
	global_load_lds_dwordx4 v[246:247], off
	s_waitcnt vmcnt(8)
	s_waitcnt lgkmcnt(0)
	s_barrier
	s_setprio 1
	v_mfma_f32_16x16x32_bf16 v[126:129], v[156:159], v[208:211], v[126:129]
	v_mfma_f32_16x16x32_bf16 v[122:125], v[168:171], v[208:211], v[122:125]
	v_mfma_f32_16x16x32_bf16 v[110:113], v[156:159], v[216:219], v[110:113]
	v_mfma_f32_16x16x32_bf16 v[106:109], v[168:171], v[216:219], v[106:109]
	v_mfma_f32_16x16x32_bf16 v[94:97], v[156:159], v[224:227], v[94:97]
	v_mfma_f32_16x16x32_bf16 v[90:93], v[168:171], v[224:227], v[90:93]
	v_mfma_f32_16x16x32_bf16 v[78:81], v[156:159], v[232:235], v[78:81]
	v_mfma_f32_16x16x32_bf16 v[74:77], v[168:171], v[232:235], v[74:77]
	s_setprio 0
	s_setprio 1
	v_mfma_f32_16x16x32_bf16 v[126:129], v[164:167], v[212:215], v[126:129]
	v_mfma_f32_16x16x32_bf16 v[122:125], v[172:175], v[212:215], v[122:125]
	v_mfma_f32_16x16x32_bf16 v[110:113], v[164:167], v[220:223], v[110:113]
	v_mfma_f32_16x16x32_bf16 v[106:109], v[172:175], v[220:223], v[106:109]
	v_mfma_f32_16x16x32_bf16 v[94:97], v[164:167], v[228:231], v[94:97]
	v_mfma_f32_16x16x32_bf16 v[90:93], v[172:175], v[228:231], v[90:93]
	v_mfma_f32_16x16x32_bf16 v[78:81], v[164:167], v[236:239], v[78:81]
	v_mfma_f32_16x16x32_bf16 v[74:77], v[172:175], v[236:239], v[74:77]
	s_setprio 0
	s_setprio 1
	v_mfma_f32_16x16x32_bf16 v[118:121], v[176:179], v[208:211], v[118:121]
	v_mfma_f32_16x16x32_bf16 v[114:117], v[184:187], v[208:211], v[114:117]
	v_mfma_f32_16x16x32_bf16 v[102:105], v[176:179], v[216:219], v[102:105]
	v_mfma_f32_16x16x32_bf16 v[98:101], v[184:187], v[216:219], v[98:101]
	v_mfma_f32_16x16x32_bf16 v[86:89], v[176:179], v[224:227], v[86:89]
	v_mfma_f32_16x16x32_bf16 v[82:85], v[184:187], v[224:227], v[82:85]
	v_mfma_f32_16x16x32_bf16 v[70:73], v[176:179], v[232:235], v[70:73]
	v_mfma_f32_16x16x32_bf16 v[66:69], v[184:187], v[232:235], v[66:69]
	s_setprio 0
	s_setprio 1
	v_mfma_f32_16x16x32_bf16 v[118:121], v[180:183], v[212:215], v[118:121]
	v_mfma_f32_16x16x32_bf16 v[114:117], v[204:207], v[212:215], v[114:117]
	v_mfma_f32_16x16x32_bf16 v[102:105], v[180:183], v[220:223], v[102:105]
	v_mfma_f32_16x16x32_bf16 v[98:101], v[204:207], v[220:223], v[98:101]
	v_mfma_f32_16x16x32_bf16 v[86:89], v[180:183], v[228:231], v[86:89]
	v_mfma_f32_16x16x32_bf16 v[82:85], v[204:207], v[228:231], v[82:85]
	v_mfma_f32_16x16x32_bf16 v[70:73], v[180:183], v[236:239], v[70:73]
	v_mfma_f32_16x16x32_bf16 v[66:69], v[204:207], v[236:239], v[66:69]
	s_setprio 0
	s_barrier
; #define PG8_STAGE(bufoff, gbase, voff) do { _Pragma("unroll") for (int _i = 0; _i < 2; ++_i) \
;         __builtin_amdgcn_global_load_lds((const unsigned*)((const char*)(gbase) + (voff)[_i]), (PG8_LAS unsigned*)(lds + (bufoff) + ldsw + _i * 8192), 16, 0, 0); } while (0)
; #define PG8_LDA(dst, b, h) do { _Pragma("unroll") for (int m = 0; m < 4; ++m) _Pragma("unroll") for (int k = 0; k < 2; ++k) dst[m][k] = *(const PG8_LAS bf16x8*)(lds + PG8_SA(b, h) + aoff + m * 2048 + k * 1024); } while (0)
; #define PG8_MMA(ai, bj, At, Bt) do { __builtin_amdgcn_s_setprio(1); _Pragma("unroll") for (int m = 0; m < 4; ++m) _Pragma("unroll") for (int n = 0; n < 2; ++n) _Pragma("unroll") for (int k = 0; k < 2; ++k) \
;         acc[ai][bj][m][n] = __builtin_amdgcn_mfma_f32_16x16x32_bf16(Bt[n][k], At[m][k], acc[ai][bj][m][n], 0, 0, 0); __builtin_amdgcn_s_setprio(0); } while (0)
; #define PG8_WAIT_V(n) asm volatile("s_waitcnt vmcnt(" #n ")" ::: "memory")
; #define PG8_WAIT_L(n) asm volatile("s_waitcnt lgkmcnt(" #n ")" ::: "memory")
; #define PG8_BAR __builtin_amdgcn_s_barrier()
; #define PG8_SCHED __builtin_amdgcn_sched_barrier(0)
; template <class Epi, class Sched, bool ALIGN_EPI = false, bool SP2 = false>
; __device__ __forceinline__ void gemm_phase(PG8_LAS unsigned char* lds, const Gemm g, const Sched& S, const Epi& E) {
;     ...
;         for (int t = 0; t < nt; t += 2) {
;     ...
;             PG8_LDA(At, 1, 1); PG8_STAGE(PG8_SB(1, 0), b3, voffB); PG8_STAGE(PG8_SB(1, 1), b3 + hstep, voffB); PG8_STAGE(PG8_SA(1, 0), a3, voffA);
;             PG8_WAIT_V(8); PG8_WAIT_L(0); PG8_BAR; PG8_MMA(1, 0, At, B0); PG8_MMA(1, 1, At, B1); PG8_BAR; PG8_SCHED;
	s_add_i32 s47, s47, s4
	v_lshl_add_u64 v[160:161], v[160:161], 0, s[68:69]
	s_mov_b32 m0, s47
	ds_read_b128 v[208:211], v163 offset:49152
	ds_read_b128 v[212:215], v163 offset:50176
	ds_read_b128 v[216:219], v163 offset:51200
	ds_read_b128 v[220:223], v163 offset:52224
	ds_read_b128 v[224:227], v163 offset:53248
	ds_read_b128 v[228:231], v163 offset:54272
	ds_read_b128 v[232:235], v163 offset:55296
	ds_read_b128 v[236:239], v163 offset:56320
	global_load_lds_dwordx4 v[160:161], off
	s_add_i32 m0, s47, 0x2000
	s_add_u32 s18, s18, 0x200080
	v_lshl_add_u64 v[160:161], v[240:241], 0, s[68:69]
	s_addc_u32 s19, s19, 0
	s_add_i32 s47, s76, s4
	global_load_lds_dwordx4 v[160:161], off
	v_lshl_add_u64 v[160:161], s[18:19], 0, v[148:149]
	s_mov_b32 m0, s47
	s_nop 0
	global_load_lds_dwordx4 v[160:161], off
	v_lshl_add_u64 v[160:161], s[18:19], 0, v[144:145]
	s_add_i32 m0, s47, 0x2000
	s_nop 0
	global_load_lds_dwordx4 v[160:161], off
	v_lshl_add_u64 v[160:161], v[242:243], 0, s[68:69]
	s_mov_b32 m0, s1
	s_nop 0
	global_load_lds_dwordx4 v[160:161], off
	v_lshl_add_u64 v[160:161], v[244:245], 0, s[68:69]
	s_mov_b32 m0, s60
	s_nop 0
	global_load_lds_dwordx4 v[160:161], off
	s_nop 0
	s_waitcnt vmcnt(8)
	s_waitcnt lgkmcnt(0)
	s_barrier
	s_setprio 1
	v_mfma_f32_16x16x32_bf16 v[62:65], v[156:159], v[208:211], v[62:65]
	v_mfma_f32_16x16x32_bf16 v[58:61], v[168:171], v[208:211], v[58:61]
	v_mfma_f32_16x16x32_bf16 v[46:49], v[156:159], v[216:219], v[46:49]
	v_mfma_f32_16x16x32_bf16 v[42:45], v[168:171], v[216:219], v[42:45]
	v_mfma_f32_16x16x32_bf16 v[30:33], v[156:159], v[224:227], v[30:33]
	v_mfma_f32_16x16x32_bf16 v[26:29], v[168:171], v[224:227], v[26:29]
	v_mfma_f32_16x16x32_bf16 v[14:17], v[156:159], v[232:235], v[14:17]
	v_mfma_f32_16x16x32_bf16 v[10:13], v[168:171], v[232:235], v[10:13]
	s_setprio 0
	s_setprio 1
	v_mfma_f32_16x16x32_bf16 v[62:65], v[164:167], v[212:215], v[62:65]
	v_mfma_f32_16x16x32_bf16 v[58:61], v[172:175], v[212:215], v[58:61]
	v_mfma_f32_16x16x32_bf16 v[46:49], v[164:167], v[220:223], v[46:49]
	v_mfma_f32_16x16x32_bf16 v[42:45], v[172:175], v[220:223], v[42:45]
	v_mfma_f32_16x16x32_bf16 v[30:33], v[164:167], v[228:231], v[30:33]
	v_mfma_f32_16x16x32_bf16 v[26:29], v[172:175], v[228:231], v[26:29]
	v_mfma_f32_16x16x32_bf16 v[14:17], v[164:167], v[236:239], v[14:17]
	v_mfma_f32_16x16x32_bf16 v[10:13], v[172:175], v[236:239], v[10:13]
	s_setprio 0
	s_setprio 1
	v_mfma_f32_16x16x32_bf16 v[54:57], v[176:179], v[208:211], v[54:57]
	v_mfma_f32_16x16x32_bf16 v[50:53], v[184:187], v[208:211], v[50:53]
	v_mfma_f32_16x16x32_bf16 v[38:41], v[176:179], v[216:219], v[38:41]
	v_mfma_f32_16x16x32_bf16 v[34:37], v[184:187], v[216:219], v[34:37]
	v_mfma_f32_16x16x32_bf16 v[22:25], v[176:179], v[224:227], v[22:25]
	v_mfma_f32_16x16x32_bf16 v[18:21], v[184:187], v[224:227], v[18:21]
	v_mfma_f32_16x16x32_bf16 v[6:9], v[176:179], v[232:235], v[6:9]
	v_mfma_f32_16x16x32_bf16 v[2:5], v[184:187], v[232:235], v[2:5]
	s_setprio 0
	s_setprio 1
	v_mfma_f32_16x16x32_bf16 v[54:57], v[180:183], v[212:215], v[54:57]
	v_mfma_f32_16x16x32_bf16 v[50:53], v[204:207], v[212:215], v[50:53]
	v_mfma_f32_16x16x32_bf16 v[38:41], v[180:183], v[220:223], v[38:41]
	v_mfma_f32_16x16x32_bf16 v[34:37], v[204:207], v[220:223], v[34:37]
	v_mfma_f32_16x16x32_bf16 v[22:25], v[180:183], v[228:231], v[22:25]
	v_mfma_f32_16x16x32_bf16 v[18:21], v[204:207], v[228:231], v[18:21]
	v_mfma_f32_16x16x32_bf16 v[6:9], v[180:183], v[236:239], v[6:9]
	v_mfma_f32_16x16x32_bf16 v[2:5], v[204:207], v[236:239], v[2:5]
	s_setprio 0
	s_barrier
	s_add_i32 s46, s46, 2
	s_add_u32 s58, s58, 0x100
	s_addc_u32 s59, s59, 0
	s_add_u32 s78, s78, 0x100
	s_addc_u32 s79, s79, 0
	s_cmpk_gt_u32 s46, 0x7d
	s_cbranch_scc0 .LBB0_36
	s_and_b64 vcc, exec, s[12:13]
	s_cbranch_vccz .LBB0_39
	s_barrier

; #define PG8_STAGE(bufoff, gbase, voff) do { _Pragma("unroll") for (int _i = 0; _i < 2; ++_i) \
;         __builtin_amdgcn_global_load_lds((const unsigned*)((const char*)(gbase) + (voff)[_i]), (PG8_LAS unsigned*)(lds + (bufoff) + ldsw + _i * 8192), 16, 0, 0); } while (0)
; #define PG8_LDA(dst, b, h) do { _Pragma("unroll") for (int m = 0; m < 4; ++m) _Pragma("unroll") for (int k = 0; k < 2; ++k) dst[m][k] = *(const PG8_LAS bf16x8*)(lds + PG8_SA(b, h) + aoff + m * 2048 + k * 1024); } while (0)
; #define PG8_LDB(dst, b, h) do { _Pragma("unroll") for (int n = 0; n < 2; ++n) _Pragma("unroll") for (int k = 0; k < 2; ++k) dst[n][k] = *(const PG8_LAS bf16x8*)(lds + PG8_SB(b, h) + boff + n * 2048 + k * 1024); } while (0)
; #define PG8_MMA(ai, bj, At, Bt) do { __builtin_amdgcn_s_setprio(1); _Pragma("unroll") for (int m = 0; m < 4; ++m) _Pragma("unroll") for (int n = 0; n < 2; ++n) _Pragma("unroll") for (int k = 0; k < 2; ++k) \
;         acc[ai][bj][m][n] = __builtin_amdgcn_mfma_f32_16x16x32_bf16(Bt[n][k], At[m][k], acc[ai][bj][m][n], 0, 0, 0); __builtin_amdgcn_s_setprio(0); } while (0)
; #define PG8_WAIT_V(n) asm volatile("s_waitcnt vmcnt(" #n ")" ::: "memory")
; #define PG8_WAIT_L(n) asm volatile("s_waitcnt lgkmcnt(" #n ")" ::: "memory")
; template <class Epi, class Sched, bool ALIGN_EPI = false, bool SP2 = false>
; __device__ __forceinline__ void gemm_phase(PG8_LAS unsigned char* lds, const Gemm g, const Sched& S, const Epi& E) {
;     ...
;             const bool last = (t == nt - 2);
;             const char* a1 = cA + (size_t)(t + 1) * kstep;
;             const char* a2 = last ? nA : cA + (size_t)(t + 2) * kstep; const char* b2 = last ? nB : cB + (size_t)(t + 2) * kstep;
;             const char* a3 = a2 + kstep; const char* b3 = b2 + kstep;
;             if (last && has_next) S.a_ready(nxt);
;             if constexpr (SP2) {
;             PG8_LDB(B0, 0, 0); PG8_LDB(B1, 0, 1); PG8_SCHED; PG8_LDA(At, 0, 0); PG8_STAGE(PG8_SA(1, 1), a1 + hstep, voffA);
;             PG8_WAIT_V(8); PG8_WAIT_L(0); PG8_BAR; PG8_MMA(0, 0, At, B0); PG8_MMA(0, 1, At, B1); PG8_BAR; PG8_SCHED;
;             PG8_LDA(At, 0, 1); PG8_STAGE(PG8_SB(0, 0), b2, voffB); PG8_STAGE(PG8_SB(0, 1), b2 + hstep, voffB); PG8_STAGE(PG8_SA(0, 0), a2, voffA);
;             PG8_WAIT_V(8); PG8_WAIT_L(0); PG8_BAR; PG8_MMA(1, 0, At, B0); PG8_MMA(1, 1, At, B1); PG8_BAR; PG8_SCHED;
.LBB0_76:
	s_add_u32 s18, s0, 0xfff80080
	s_addc_u32 s19, s1, -1
	s_add_i32 s47, 0, 0x10000
	s_cmp_eq_u32 s46, 28
	s_cselect_b32 s59, s60, s19
	s_cselect_b32 s58, s73, s18
	v_add_u32_e32 v158, s47, v143
	s_cselect_b32 s19, s45, s79
	s_cselect_b32 s18, s84, s78
	s_add_i32 s80, 0, 0x14000
	ds_read_b128 v[162:165], v158
	ds_read_b128 v[166:169], v158 offset:1024
	ds_read_b128 v[170:173], v158 offset:2048
	ds_read_b128 v[174:177], v158 offset:3072
	v_add_u32_e32 v158, s80, v143
	ds_read_b128 v[178:181], v158
	ds_read_b128 v[182:185], v158 offset:1024
	ds_read_b128 v[204:207], v158 offset:2048
	ds_read_b128 v[208:211], v158 offset:3072
	v_lshl_add_u64 v[158:159], s[0:1], 0, v[154:155]
	s_add_i32 m0, s62, 0xc000
	ds_read_b128 v[212:215], v161
	ds_read_b128 v[216:219], v161 offset:1024
	ds_read_b128 v[220:223], v161 offset:2048
	ds_read_b128 v[224:227], v161 offset:3072
	ds_read_b128 v[228:231], v161 offset:4096
	ds_read_b128 v[232:235], v161 offset:5120
	ds_read_b128 v[236:239], v161 offset:6144
	ds_read_b128 v[240:243], v161 offset:7168
	global_load_lds_dwordx4 v[158:159], off
	v_lshl_add_u64 v[158:159], s[0:1], 0, v[156:157]
	s_add_i32 m0, s62, 0xe000
	s_nop 0
	global_load_lds_dwordx4 v[158:159], off
	s_nop 0
	s_waitcnt vmcnt(8)
	s_waitcnt lgkmcnt(0)
	s_barrier
	s_setprio 1
	v_mfma_f32_16x16x32_bf16 v[126:129], v[162:165], v[212:215], v[126:129]
	v_mfma_f32_16x16x32_bf16 v[122:125], v[170:173], v[212:215], v[122:125]
	v_mfma_f32_16x16x32_bf16 v[110:113], v[162:165], v[220:223], v[110:113]
	v_mfma_f32_16x16x32_bf16 v[106:109], v[170:173], v[220:223], v[106:109]
	v_mfma_f32_16x16x32_bf16 v[94:97], v[162:165], v[228:231], v[94:97]
	v_mfma_f32_16x16x32_bf16 v[90:93], v[170:173], v[228:231], v[90:93]
	v_mfma_f32_16x16x32_bf16 v[78:81], v[162:165], v[236:239], v[78:81]
	v_mfma_f32_16x16x32_bf16 v[74:77], v[170:173], v[236:239], v[74:77]
	s_setprio 0
	s_setprio 1
	v_mfma_f32_16x16x32_bf16 v[126:129], v[166:169], v[216:219], v[126:129]
	v_mfma_f32_16x16x32_bf16 v[122:125], v[174:177], v[216:219], v[122:125]
	v_mfma_f32_16x16x32_bf16 v[110:113], v[166:169], v[224:227], v[110:113]
	v_mfma_f32_16x16x32_bf16 v[106:109], v[174:177], v[224:227], v[106:109]
	v_mfma_f32_16x16x32_bf16 v[94:97], v[166:169], v[232:235], v[94:97]
	v_mfma_f32_16x16x32_bf16 v[90:93], v[174:177], v[232:235], v[90:93]
	v_mfma_f32_16x16x32_bf16 v[78:81], v[166:169], v[240:243], v[78:81]
	v_mfma_f32_16x16x32_bf16 v[74:77], v[174:177], v[240:243], v[74:77]
	s_setprio 0
	s_setprio 1
	v_mfma_f32_16x16x32_bf16 v[118:121], v[178:181], v[212:215], v[118:121]
	v_mfma_f32_16x16x32_bf16 v[114:117], v[204:207], v[212:215], v[114:117]
	v_mfma_f32_16x16x32_bf16 v[102:105], v[178:181], v[220:223], v[102:105]
	v_mfma_f32_16x16x32_bf16 v[98:101], v[204:207], v[220:223], v[98:101]
	v_mfma_f32_16x16x32_bf16 v[86:89], v[178:181], v[228:231], v[86:89]
	v_mfma_f32_16x16x32_bf16 v[82:85], v[204:207], v[228:231], v[82:85]
	v_mfma_f32_16x16x32_bf16 v[70:73], v[178:181], v[236:239], v[70:73]
	v_mfma_f32_16x16x32_bf16 v[66:69], v[204:207], v[236:239], v[66:69]
	s_setprio 0
	s_setprio 1
	v_mfma_f32_16x16x32_bf16 v[118:121], v[182:185], v[216:219], v[118:121]
	v_mfma_f32_16x16x32_bf16 v[114:117], v[208:211], v[216:219], v[114:117]
	v_mfma_f32_16x16x32_bf16 v[102:105], v[182:185], v[224:227], v[102:105]
	v_mfma_f32_16x16x32_bf16 v[98:101], v[208:211], v[224:227], v[98:101]
	v_mfma_f32_16x16x32_bf16 v[86:89], v[182:185], v[232:235], v[86:89]
	v_mfma_f32_16x16x32_bf16 v[82:85], v[208:211], v[232:235], v[82:85]
	v_mfma_f32_16x16x32_bf16 v[70:73], v[182:185], v[240:243], v[70:73]
	v_mfma_f32_16x16x32_bf16 v[66:69], v[208:211], v[240:243], v[66:69]
	s_setprio 0
	s_barrier
	s_add_i32 s47, s47, s54
	v_lshl_add_u64 v[158:159], s[18:19], 0, v[148:149]
	s_mov_b32 m0, s47
	ds_read_b128 v[212:215], v161 offset:16384
	ds_read_b128 v[216:219], v161 offset:17408
	ds_read_b128 v[220:223], v161 offset:18432
	ds_read_b128 v[224:227], v161 offset:19456
	ds_read_b128 v[228:231], v161 offset:20480
	ds_read_b128 v[232:235], v161 offset:21504
	ds_read_b128 v[236:239], v161 offset:22528
	ds_read_b128 v[240:243], v161 offset:23552
	global_load_lds_dwordx4 v[158:159], off
	s_add_i32 m0, s47, 0x2000
	s_add_u32 s76, s18, 0x80000
	v_lshl_add_u64 v[186:187], s[18:19], 0, v[144:145]
	s_addc_u32 s77, s19, 0
	s_add_i32 s47, s80, s54
	global_load_lds_dwordx4 v[186:187], off
	v_lshl_add_u64 v[244:245], s[76:77], 0, v[148:149]
	s_mov_b32 m0, s47
	v_lshl_add_u64 v[246:247], s[58:59], 0, v[146:147]
	global_load_lds_dwordx4 v[244:245], off
	v_lshl_add_u64 v[244:245], s[76:77], 0, v[144:145]
	s_add_i32 m0, s47, 0x2000
	s_nop 0
	global_load_lds_dwordx4 v[244:245], off
	v_lshl_add_u64 v[244:245], s[58:59], 0, v[150:151]
	s_mov_b32 m0, s62
	s_nop 0
	global_load_lds_dwordx4 v[244:245], off
	s_mov_b32 m0, s63
	s_nop 0
	global_load_lds_dwordx4 v[246:247], off
	s_waitcnt vmcnt(8)
	s_waitcnt lgkmcnt(0)
	s_barrier
; #define PG8_STAGE(bufoff, gbase, voff) do { _Pragma("unroll") for (int _i = 0; _i < 2; ++_i) \
;         __builtin_amdgcn_global_load_lds((const unsigned*)((const char*)(gbase) + (voff)[_i]), (PG8_LAS unsigned*)(lds + (bufoff) + ldsw + _i * 8192), 16, 0, 0); } while (0)
; #define PG8_LDA(dst, b, h) do { _Pragma("unroll") for (int m = 0; m < 4; ++m) _Pragma("unroll") for (int k = 0; k < 2; ++k) dst[m][k] = *(const PG8_LAS bf16x8*)(lds + PG8_SA(b, h) + aoff + m * 2048 + k * 1024); } while (0)
; #define PG8_LDB(dst, b, h) do { _Pragma("unroll") for (int n = 0; n < 2; ++n) _Pragma("unroll") for (int k = 0; k < 2; ++k) dst[n][k] = *(const PG8_LAS bf16x8*)(lds + PG8_SB(b, h) + boff + n * 2048 + k * 1024); } while (0)
; #define PG8_MMA(ai, bj, At, Bt) do { __builtin_amdgcn_s_setprio(1); _Pragma("unroll") for (int m = 0; m < 4; ++m) _Pragma("unroll") for (int n = 0; n < 2; ++n) _Pragma("unroll") for (int k = 0; k < 2; ++k) \
;         acc[ai][bj][m][n] = __builtin_amdgcn_mfma_f32_16x16x32_bf16(Bt[n][k], At[m][k], acc[ai][bj][m][n], 0, 0, 0); __builtin_amdgcn_s_setprio(0); } while (0)
; #define PG8_WAIT_V(n) asm volatile("s_waitcnt vmcnt(" #n ")" ::: "memory")
; #define PG8_WAIT_L(n) asm volatile("s_waitcnt lgkmcnt(" #n ")" ::: "memory")
; #define PG8_BAR __builtin_amdgcn_s_barrier()
; #define PG8_SCHED __builtin_amdgcn_sched_barrier(0)
; template <class Epi, class Sched, bool ALIGN_EPI = false, bool SP2 = false>
; __device__ __forceinline__ void gemm_phase(PG8_LAS unsigned char* lds, const Gemm g, const Sched& S, const Epi& E) {
;     ...
;             PG8_WAIT_V(8); PG8_WAIT_L(0); PG8_BAR; PG8_MMA(1, 0, At, B0); PG8_MMA(1, 1, At, B1); PG8_BAR; PG8_SCHED;
;             PG8_LDB(B0, 1, 0); PG8_LDB(B1, 1, 1); PG8_SCHED; PG8_LDA(At, 1, 0); PG8_STAGE(PG8_SA(0, 1), a2 + hstep, voffA);
;             PG8_WAIT_V(8); PG8_WAIT_L(0); PG8_BAR; PG8_MMA(0, 0, At, B0); PG8_MMA(0, 1, At, B1); PG8_BAR; PG8_SCHED;
;             PG8_LDA(At, 1, 1); PG8_STAGE(PG8_SB(1, 0), b3, voffB); PG8_STAGE(PG8_SB(1, 1), b3 + hstep, voffB); PG8_STAGE(PG8_SA(1, 0), a3, voffA);
;             PG8_WAIT_V(8); PG8_WAIT_L(0); PG8_BAR; PG8_MMA(1, 0, At, B0); PG8_MMA(1, 1, At, B1); PG8_BAR; PG8_SCHED;
	s_setprio 1
	v_mfma_f32_16x16x32_bf16 v[62:65], v[162:165], v[212:215], v[62:65]
	v_mfma_f32_16x16x32_bf16 v[58:61], v[170:173], v[212:215], v[58:61]
	v_mfma_f32_16x16x32_bf16 v[46:49], v[162:165], v[220:223], v[46:49]
	v_mfma_f32_16x16x32_bf16 v[42:45], v[170:173], v[220:223], v[42:45]
	v_mfma_f32_16x16x32_bf16 v[30:33], v[162:165], v[228:231], v[30:33]
	v_mfma_f32_16x16x32_bf16 v[26:29], v[170:173], v[228:231], v[26:29]
	v_mfma_f32_16x16x32_bf16 v[14:17], v[162:165], v[236:239], v[14:17]
	v_mfma_f32_16x16x32_bf16 v[10:13], v[170:173], v[236:239], v[10:13]
	s_setprio 0
	s_setprio 1
	v_mfma_f32_16x16x32_bf16 v[62:65], v[166:169], v[216:219], v[62:65]
	v_mfma_f32_16x16x32_bf16 v[58:61], v[174:177], v[216:219], v[58:61]
	v_mfma_f32_16x16x32_bf16 v[46:49], v[166:169], v[224:227], v[46:49]
	v_mfma_f32_16x16x32_bf16 v[42:45], v[174:177], v[224:227], v[42:45]
	v_mfma_f32_16x16x32_bf16 v[30:33], v[166:169], v[232:235], v[30:33]
	v_mfma_f32_16x16x32_bf16 v[26:29], v[174:177], v[232:235], v[26:29]
	v_mfma_f32_16x16x32_bf16 v[14:17], v[166:169], v[240:243], v[14:17]
	v_mfma_f32_16x16x32_bf16 v[10:13], v[174:177], v[240:243], v[10:13]
	s_setprio 0
	s_setprio 1
	v_mfma_f32_16x16x32_bf16 v[54:57], v[178:181], v[212:215], v[54:57]
	v_mfma_f32_16x16x32_bf16 v[50:53], v[204:207], v[212:215], v[50:53]
	v_mfma_f32_16x16x32_bf16 v[38:41], v[178:181], v[220:223], v[38:41]
	v_mfma_f32_16x16x32_bf16 v[34:37], v[204:207], v[220:223], v[34:37]
	v_mfma_f32_16x16x32_bf16 v[22:25], v[178:181], v[228:231], v[22:25]
	v_mfma_f32_16x16x32_bf16 v[18:21], v[204:207], v[228:231], v[18:21]
	v_mfma_f32_16x16x32_bf16 v[6:9], v[178:181], v[236:239], v[6:9]
	v_mfma_f32_16x16x32_bf16 v[2:5], v[204:207], v[236:239], v[2:5]
	s_setprio 0
	s_setprio 1
	v_mfma_f32_16x16x32_bf16 v[54:57], v[182:185], v[216:219], v[54:57]
	v_mfma_f32_16x16x32_bf16 v[50:53], v[208:211], v[216:219], v[50:53]
	v_mfma_f32_16x16x32_bf16 v[38:41], v[182:185], v[224:227], v[38:41]
	v_mfma_f32_16x16x32_bf16 v[34:37], v[208:211], v[224:227], v[34:37]
	v_mfma_f32_16x16x32_bf16 v[22:25], v[182:185], v[232:235], v[22:25]
	v_mfma_f32_16x16x32_bf16 v[18:21], v[208:211], v[232:235], v[18:21]
	v_mfma_f32_16x16x32_bf16 v[6:9], v[182:185], v[240:243], v[6:9]
	v_mfma_f32_16x16x32_bf16 v[2:5], v[208:211], v[240:243], v[2:5]
	s_setprio 0
	s_barrier
	s_add_i32 s47, 0, 0x18000
	s_add_i32 s76, 0, 0x1c000
	v_add_u32_e32 v174, s47, v143
	v_add_u32_e32 v203, s76, v143
	ds_read_b128 v[162:165], v174
	ds_read_b128 v[166:169], v174 offset:1024
	ds_read_b128 v[170:173], v174 offset:2048
	ds_read_b128 v[174:177], v174 offset:3072
	ds_read_b128 v[178:181], v203
	ds_read_b128 v[182:185], v203 offset:1024
	ds_read_b128 v[204:207], v203 offset:2048
	ds_read_b128 v[208:211], v203 offset:3072
	s_add_u32 s58, s58, 0x80000
	s_addc_u32 s59, s59, 0
	s_mov_b32 m0, s67
	v_lshl_add_u64 v[248:249], s[58:59], 0, v[150:151]
	ds_read_b128 v[212:215], v161 offset:32768
	ds_read_b128 v[216:219], v161 offset:33792
	ds_read_b128 v[220:223], v161 offset:34816
	ds_read_b128 v[224:227], v161 offset:35840
	ds_read_b128 v[228:231], v161 offset:36864
	ds_read_b128 v[232:235], v161 offset:37888
	ds_read_b128 v[236:239], v161 offset:38912
	ds_read_b128 v[240:243], v161 offset:39936
	global_load_lds_dwordx4 v[248:249], off
	v_lshl_add_u64 v[248:249], s[58:59], 0, v[146:147]
	s_mov_b32 m0, s4
	s_nop 0
	global_load_lds_dwordx4 v[248:249], off
	s_waitcnt vmcnt(8)
	s_waitcnt lgkmcnt(0)
	s_barrier
	s_setprio 1
	v_mfma_f32_16x16x32_bf16 v[126:129], v[162:165], v[212:215], v[126:129]
	v_mfma_f32_16x16x32_bf16 v[122:125], v[170:173], v[212:215], v[122:125]
	v_mfma_f32_16x16x32_bf16 v[110:113], v[162:165], v[220:223], v[110:113]
	v_mfma_f32_16x16x32_bf16 v[106:109], v[170:173], v[220:223], v[106:109]
	v_mfma_f32_16x16x32_bf16 v[94:97], v[162:165], v[228:231], v[94:97]
	v_mfma_f32_16x16x32_bf16 v[90:93], v[170:173], v[228:231], v[90:93]
	v_mfma_f32_16x16x32_bf16 v[78:81], v[162:165], v[236:239], v[78:81]
	v_mfma_f32_16x16x32_bf16 v[74:77], v[170:173], v[236:239], v[74:77]
	s_setprio 0
	s_setprio 1
	v_mfma_f32_16x16x32_bf16 v[126:129], v[166:169], v[216:219], v[126:129]
	v_mfma_f32_16x16x32_bf16 v[122:125], v[174:177], v[216:219], v[122:125]
	v_mfma_f32_16x16x32_bf16 v[110:113], v[166:169], v[224:227], v[110:113]
	v_mfma_f32_16x16x32_bf16 v[106:109], v[174:177], v[224:227], v[106:109]
	v_mfma_f32_16x16x32_bf16 v[94:97], v[166:169], v[232:235], v[94:97]
	v_mfma_f32_16x16x32_bf16 v[90:93], v[174:177], v[232:235], v[90:93]
	v_mfma_f32_16x16x32_bf16 v[78:81], v[166:169], v[240:243], v[78:81]
	v_mfma_f32_16x16x32_bf16 v[74:77], v[174:177], v[240:243], v[74:77]
	s_setprio 0
	s_setprio 1
	v_mfma_f32_16x16x32_bf16 v[118:121], v[178:181], v[212:215], v[118:121]
	v_mfma_f32_16x16x32_bf16 v[114:117], v[204:207], v[212:215], v[114:117]
	v_mfma_f32_16x16x32_bf16 v[102:105], v[178:181], v[220:223], v[102:105]
	v_mfma_f32_16x16x32_bf16 v[98:101], v[204:207], v[220:223], v[98:101]
	v_mfma_f32_16x16x32_bf16 v[86:89], v[178:181], v[228:231], v[86:89]
	v_mfma_f32_16x16x32_bf16 v[82:85], v[204:207], v[228:231], v[82:85]
	v_mfma_f32_16x16x32_bf16 v[70:73], v[178:181], v[236:239], v[70:73]
	v_mfma_f32_16x16x32_bf16 v[66:69], v[204:207], v[236:239], v[66:69]
	s_setprio 0
	s_setprio 1
	v_mfma_f32_16x16x32_bf16 v[118:121], v[182:185], v[216:219], v[118:121]
	v_mfma_f32_16x16x32_bf16 v[114:117], v[208:211], v[216:219], v[114:117]
	v_mfma_f32_16x16x32_bf16 v[102:105], v[182:185], v[224:227], v[102:105]
	v_mfma_f32_16x16x32_bf16 v[98:101], v[208:211], v[224:227], v[98:101]
	v_mfma_f32_16x16x32_bf16 v[86:89], v[182:185], v[232:235], v[86:89]
	v_mfma_f32_16x16x32_bf16 v[82:85], v[208:211], v[232:235], v[82:85]
	v_mfma_f32_16x16x32_bf16 v[70:73], v[182:185], v[240:243], v[70:73]
	v_mfma_f32_16x16x32_bf16 v[66:69], v[208:211], v[240:243], v[66:69]
	s_setprio 0
	s_barrier
; #define PG8_STAGE(bufoff, gbase, voff) do { _Pragma("unroll") for (int _i = 0; _i < 2; ++_i) \
;         __builtin_amdgcn_global_load_lds((const unsigned*)((const char*)(gbase) + (voff)[_i]), (PG8_LAS unsigned*)(lds + (bufoff) + ldsw + _i * 8192), 16, 0, 0); } while (0)
; #define PG8_LDA(dst, b, h) do { _Pragma("unroll") for (int m = 0; m < 4; ++m) _Pragma("unroll") for (int k = 0; k < 2; ++k) dst[m][k] = *(const PG8_LAS bf16x8*)(lds + PG8_SA(b, h) + aoff + m * 2048 + k * 1024); } while (0)
; #define PG8_MMA(ai, bj, At, Bt) do { __builtin_amdgcn_s_setprio(1); _Pragma("unroll") for (int m = 0; m < 4; ++m) _Pragma("unroll") for (int n = 0; n < 2; ++n) _Pragma("unroll") for (int k = 0; k < 2; ++k) \
;         acc[ai][bj][m][n] = __builtin_amdgcn_mfma_f32_16x16x32_bf16(Bt[n][k], At[m][k], acc[ai][bj][m][n], 0, 0, 0); __builtin_amdgcn_s_setprio(0); } while (0)
; #define PG8_WAIT_V(n) asm volatile("s_waitcnt vmcnt(" #n ")" ::: "memory")
; #define PG8_WAIT_L(n) asm volatile("s_waitcnt lgkmcnt(" #n ")" ::: "memory")
; #define PG8_BAR __builtin_amdgcn_s_barrier()
; #define PG8_SCHED __builtin_amdgcn_sched_barrier(0)
; template <class Epi, class Sched, bool ALIGN_EPI = false, bool SP2 = false>
; __device__ __forceinline__ void gemm_phase(PG8_LAS unsigned char* lds, const Gemm g, const Sched& S, const Epi& E) {
;     ...
;         for (int t = 0; t < nt; t += 2) {
;     ...
;             PG8_LDA(At, 1, 1); PG8_STAGE(PG8_SB(1, 0), b3, voffB); PG8_STAGE(PG8_SB(1, 1), b3 + hstep, voffB); PG8_STAGE(PG8_SA(1, 0), a3, voffA);
;             PG8_WAIT_V(8); PG8_WAIT_L(0); PG8_BAR; PG8_MMA(1, 0, At, B0); PG8_MMA(1, 1, At, B1); PG8_BAR; PG8_SCHED;
	s_add_i32 s47, s47, s54
	v_lshl_add_u64 v[158:159], v[158:159], 0, s[68:69]
	s_mov_b32 m0, s47
	ds_read_b128 v[212:215], v161 offset:49152
	ds_read_b128 v[216:219], v161 offset:50176
	ds_read_b128 v[220:223], v161 offset:51200
	ds_read_b128 v[224:227], v161 offset:52224
	ds_read_b128 v[228:231], v161 offset:53248
	ds_read_b128 v[232:235], v161 offset:54272
	ds_read_b128 v[236:239], v161 offset:55296
	ds_read_b128 v[240:243], v161 offset:56320
	global_load_lds_dwordx4 v[158:159], off
	s_add_i32 m0, s47, 0x2000
	s_add_u32 s18, s18, 0x80080
	v_lshl_add_u64 v[158:159], v[186:187], 0, s[68:69]
	s_addc_u32 s19, s19, 0
	s_add_i32 s47, s76, s54
	global_load_lds_dwordx4 v[158:159], off
	v_lshl_add_u64 v[158:159], s[18:19], 0, v[148:149]
	s_mov_b32 m0, s47
	s_nop 0
	global_load_lds_dwordx4 v[158:159], off
	v_lshl_add_u64 v[158:159], s[18:19], 0, v[144:145]
	s_add_i32 m0, s47, 0x2000
	s_nop 0
	global_load_lds_dwordx4 v[158:159], off
	v_lshl_add_u64 v[158:159], v[244:245], 0, s[68:69]
	s_mov_b32 m0, s5
	s_nop 0
	global_load_lds_dwordx4 v[158:159], off
	v_lshl_add_u64 v[158:159], v[246:247], 0, s[68:69]
	s_mov_b32 m0, s57
	s_nop 0
	global_load_lds_dwordx4 v[158:159], off
	s_nop 0
	s_waitcnt vmcnt(8)
	s_waitcnt lgkmcnt(0)
	s_barrier
	s_setprio 1
	v_mfma_f32_16x16x32_bf16 v[62:65], v[162:165], v[212:215], v[62:65]
	v_mfma_f32_16x16x32_bf16 v[58:61], v[170:173], v[212:215], v[58:61]
	v_mfma_f32_16x16x32_bf16 v[46:49], v[162:165], v[220:223], v[46:49]
	v_mfma_f32_16x16x32_bf16 v[42:45], v[170:173], v[220:223], v[42:45]
	v_mfma_f32_16x16x32_bf16 v[30:33], v[162:165], v[228:231], v[30:33]
	v_mfma_f32_16x16x32_bf16 v[26:29], v[170:173], v[228:231], v[26:29]
	v_mfma_f32_16x16x32_bf16 v[14:17], v[162:165], v[236:239], v[14:17]
	v_mfma_f32_16x16x32_bf16 v[10:13], v[170:173], v[236:239], v[10:13]
	s_setprio 0
	s_setprio 1
	v_mfma_f32_16x16x32_bf16 v[62:65], v[166:169], v[216:219], v[62:65]
	v_mfma_f32_16x16x32_bf16 v[58:61], v[174:177], v[216:219], v[58:61]
	v_mfma_f32_16x16x32_bf16 v[46:49], v[166:169], v[224:227], v[46:49]
	v_mfma_f32_16x16x32_bf16 v[42:45], v[174:177], v[224:227], v[42:45]
	v_mfma_f32_16x16x32_bf16 v[30:33], v[166:169], v[232:235], v[30:33]
	v_mfma_f32_16x16x32_bf16 v[26:29], v[174:177], v[232:235], v[26:29]
	v_mfma_f32_16x16x32_bf16 v[14:17], v[166:169], v[240:243], v[14:17]
	v_mfma_f32_16x16x32_bf16 v[10:13], v[174:177], v[240:243], v[10:13]
	s_setprio 0
	s_setprio 1
	v_mfma_f32_16x16x32_bf16 v[54:57], v[178:181], v[212:215], v[54:57]
	v_mfma_f32_16x16x32_bf16 v[50:53], v[204:207], v[212:215], v[50:53]
	v_mfma_f32_16x16x32_bf16 v[38:41], v[178:181], v[220:223], v[38:41]
	v_mfma_f32_16x16x32_bf16 v[34:37], v[204:207], v[220:223], v[34:37]
	v_mfma_f32_16x16x32_bf16 v[22:25], v[178:181], v[228:231], v[22:25]
	v_mfma_f32_16x16x32_bf16 v[18:21], v[204:207], v[228:231], v[18:21]
	v_mfma_f32_16x16x32_bf16 v[6:9], v[178:181], v[236:239], v[6:9]
	v_mfma_f32_16x16x32_bf16 v[2:5], v[204:207], v[236:239], v[2:5]
	s_setprio 0
	s_setprio 1
	v_mfma_f32_16x16x32_bf16 v[54:57], v[182:185], v[216:219], v[54:57]
	v_mfma_f32_16x16x32_bf16 v[50:53], v[208:211], v[216:219], v[50:53]
	v_mfma_f32_16x16x32_bf16 v[38:41], v[182:185], v[224:227], v[38:41]
	v_mfma_f32_16x16x32_bf16 v[34:37], v[208:211], v[224:227], v[34:37]
	v_mfma_f32_16x16x32_bf16 v[22:25], v[182:185], v[232:235], v[22:25]
	v_mfma_f32_16x16x32_bf16 v[18:21], v[208:211], v[232:235], v[18:21]
	v_mfma_f32_16x16x32_bf16 v[6:9], v[182:185], v[240:243], v[6:9]
	v_mfma_f32_16x16x32_bf16 v[2:5], v[208:211], v[240:243], v[2:5]
	s_setprio 0
	s_barrier
	s_add_i32 s46, s46, 2
	s_add_u32 s0, s0, 0x100
	s_addc_u32 s1, s1, 0
	s_add_u32 s78, s78, 0x100
	s_addc_u32 s79, s79, 0
	s_cmp_gt_u32 s46, 29
	s_cbranch_scc0 .LBB0_76
	s_and_b64 vcc, exec, s[42:43]
	s_cbranch_vccz .LBB0_79
	s_barrier

; #define PG8_STAGE(bufoff, gbase, voff) do { _Pragma("unroll") for (int _i = 0; _i < 2; ++_i) \
;         __builtin_amdgcn_global_load_lds((const unsigned*)((const char*)(gbase) + (voff)[_i]), (PG8_LAS unsigned*)(lds + (bufoff) + ldsw + _i * 8192), 16, 0, 0); } while (0)
; #define PG8_LDA(dst, b, h) do { _Pragma("unroll") for (int m = 0; m < 4; ++m) _Pragma("unroll") for (int k = 0; k < 2; ++k) dst[m][k] = *(const PG8_LAS bf16x8*)(lds + PG8_SA(b, h) + aoff + m * 2048 + k * 1024); } while (0)
; #define PG8_LDB(dst, b, h) do { _Pragma("unroll") for (int n = 0; n < 2; ++n) _Pragma("unroll") for (int k = 0; k < 2; ++k) dst[n][k] = *(const PG8_LAS bf16x8*)(lds + PG8_SB(b, h) + boff + n * 2048 + k * 1024); } while (0)
; #define PG8_MMA(ai, bj, At, Bt) do { __builtin_amdgcn_s_setprio(1); _Pragma("unroll") for (int m = 0; m < 4; ++m) _Pragma("unroll") for (int n = 0; n < 2; ++n) _Pragma("unroll") for (int k = 0; k < 2; ++k) \
;         acc[ai][bj][m][n] = __builtin_amdgcn_mfma_f32_16x16x32_bf16(Bt[n][k], At[m][k], acc[ai][bj][m][n], 0, 0, 0); __builtin_amdgcn_s_setprio(0); } while (0)
; #define PG8_WAIT_V(n) asm volatile("s_waitcnt vmcnt(" #n ")" ::: "memory")
; #define PG8_WAIT_L(n) asm volatile("s_waitcnt lgkmcnt(" #n ")" ::: "memory")
; template <class Epi, class Sched, bool ALIGN_EPI = false, bool SP2 = false>
; __device__ __forceinline__ void gemm_phase(PG8_LAS unsigned char* lds, const Gemm g, const Sched& S, const Epi& E) {
;     ...
;             const bool last = (t == nt - 2);
;             const char* a1 = cA + (size_t)(t + 1) * kstep;
;             const char* a2 = last ? nA : cA + (size_t)(t + 2) * kstep; const char* b2 = last ? nB : cB + (size_t)(t + 2) * kstep;
;             const char* a3 = a2 + kstep; const char* b3 = b2 + kstep;
;             if (last && has_next) S.a_ready(nxt);
;             if constexpr (SP2) {
;             PG8_LDB(B0, 0, 0); PG8_LDB(B1, 0, 1); PG8_SCHED; PG8_LDA(At, 0, 0); PG8_STAGE(PG8_SA(1, 1), a1 + hstep, voffA);
;             PG8_WAIT_V(8); PG8_WAIT_L(0); PG8_BAR; PG8_MMA(0, 0, At, B0); PG8_MMA(0, 1, At, B1); PG8_BAR; PG8_SCHED;
;             PG8_LDA(At, 0, 1); PG8_STAGE(PG8_SB(0, 0), b2, voffB); PG8_STAGE(PG8_SB(0, 1), b2 + hstep, voffB); PG8_STAGE(PG8_SA(0, 0), a2, voffA);
;             PG8_WAIT_V(8); PG8_WAIT_L(0); PG8_BAR; PG8_MMA(1, 0, At, B0); PG8_MMA(1, 1, At, B1); PG8_BAR; PG8_SCHED;
.LBB0_98:
	s_add_u32 s40, vcc_lo, 0xfff80080
	s_addc_u32 s41, vcc_hi, -1
	s_add_i32 s47, 0, 0x10000
	s_cmp_eq_u32 s46, 28
	s_cselect_b32 s59, s97, s41
	s_cselect_b32 s58, s84, s40
	s_cselect_b32 s41, s85, s79
	s_cselect_b32 s40, s95, s78
	s_add_i32 s80, 0, 0x14000
	v_add_u32_e32 v170, s47, v143
	v_add_u32_e32 v186, s80, v143
	ds_read_b128 v[156:159], v170
	ds_read_b128 v[162:165], v170 offset:1024
	ds_read_b128 v[166:169], v170 offset:2048
	ds_read_b128 v[170:173], v170 offset:3072
	ds_read_b128 v[174:177], v186
	ds_read_b128 v[178:181], v186 offset:1024
	ds_read_b128 v[182:185], v186 offset:2048
	ds_read_b128 v[204:207], v186 offset:3072
	v_lshl_add_u64 v[186:187], vcc, 0, v[152:153]
	s_add_i32 m0, s5, 0xc000
	ds_read_b128 v[208:211], v161
	ds_read_b128 v[212:215], v161 offset:1024
	ds_read_b128 v[216:219], v161 offset:2048
	ds_read_b128 v[220:223], v161 offset:3072
	ds_read_b128 v[224:227], v161 offset:4096
	ds_read_b128 v[228:231], v161 offset:5120
	ds_read_b128 v[232:235], v161 offset:6144
	ds_read_b128 v[236:239], v161 offset:7168
	global_load_lds_dwordx4 v[186:187], off
	v_lshl_add_u64 v[186:187], vcc, 0, v[154:155]
	s_add_i32 m0, s5, 0xe000
	s_nop 0
	global_load_lds_dwordx4 v[186:187], off
	s_waitcnt vmcnt(8)
	s_waitcnt lgkmcnt(0)
	s_barrier
	s_setprio 1
	v_mfma_f32_16x16x32_bf16 v[126:129], v[156:159], v[208:211], v[126:129]
	v_mfma_f32_16x16x32_bf16 v[122:125], v[166:169], v[208:211], v[122:125]
	v_mfma_f32_16x16x32_bf16 v[110:113], v[156:159], v[216:219], v[110:113]
	v_mfma_f32_16x16x32_bf16 v[106:109], v[166:169], v[216:219], v[106:109]
	v_mfma_f32_16x16x32_bf16 v[94:97], v[156:159], v[224:227], v[94:97]
	v_mfma_f32_16x16x32_bf16 v[90:93], v[166:169], v[224:227], v[90:93]
	v_mfma_f32_16x16x32_bf16 v[78:81], v[156:159], v[232:235], v[78:81]
	v_mfma_f32_16x16x32_bf16 v[74:77], v[166:169], v[232:235], v[74:77]
	s_setprio 0
	s_setprio 1
	v_mfma_f32_16x16x32_bf16 v[126:129], v[162:165], v[212:215], v[126:129]
	v_mfma_f32_16x16x32_bf16 v[122:125], v[170:173], v[212:215], v[122:125]
	v_mfma_f32_16x16x32_bf16 v[110:113], v[162:165], v[220:223], v[110:113]
	v_mfma_f32_16x16x32_bf16 v[106:109], v[170:173], v[220:223], v[106:109]
	v_mfma_f32_16x16x32_bf16 v[94:97], v[162:165], v[228:231], v[94:97]
	v_mfma_f32_16x16x32_bf16 v[90:93], v[170:173], v[228:231], v[90:93]
	v_mfma_f32_16x16x32_bf16 v[78:81], v[162:165], v[236:239], v[78:81]
	v_mfma_f32_16x16x32_bf16 v[74:77], v[170:173], v[236:239], v[74:77]
	s_setprio 0
	s_setprio 1
	v_mfma_f32_16x16x32_bf16 v[118:121], v[174:177], v[208:211], v[118:121]
	v_mfma_f32_16x16x32_bf16 v[114:117], v[182:185], v[208:211], v[114:117]
	v_mfma_f32_16x16x32_bf16 v[102:105], v[174:177], v[216:219], v[102:105]
	v_mfma_f32_16x16x32_bf16 v[98:101], v[182:185], v[216:219], v[98:101]
	v_mfma_f32_16x16x32_bf16 v[86:89], v[174:177], v[224:227], v[86:89]
	v_mfma_f32_16x16x32_bf16 v[82:85], v[182:185], v[224:227], v[82:85]
	v_mfma_f32_16x16x32_bf16 v[70:73], v[174:177], v[232:235], v[70:73]
	v_mfma_f32_16x16x32_bf16 v[66:69], v[182:185], v[232:235], v[66:69]
	s_setprio 0
	s_setprio 1
	v_mfma_f32_16x16x32_bf16 v[118:121], v[178:181], v[212:215], v[118:121]
	v_mfma_f32_16x16x32_bf16 v[114:117], v[204:207], v[212:215], v[114:117]
	v_mfma_f32_16x16x32_bf16 v[102:105], v[178:181], v[220:223], v[102:105]
	v_mfma_f32_16x16x32_bf16 v[98:101], v[204:207], v[220:223], v[98:101]
	v_mfma_f32_16x16x32_bf16 v[86:89], v[178:181], v[228:231], v[86:89]
	v_mfma_f32_16x16x32_bf16 v[82:85], v[204:207], v[228:231], v[82:85]
	v_mfma_f32_16x16x32_bf16 v[70:73], v[178:181], v[236:239], v[70:73]
	v_mfma_f32_16x16x32_bf16 v[66:69], v[204:207], v[236:239], v[66:69]
	s_setprio 0
	s_barrier
	s_add_i32 s47, s47, s4
	v_lshl_add_u64 v[186:187], s[40:41], 0, v[148:149]
	s_mov_b32 m0, s47
	ds_read_b128 v[208:211], v161 offset:16384
	ds_read_b128 v[212:215], v161 offset:17408
	ds_read_b128 v[216:219], v161 offset:18432
	ds_read_b128 v[220:223], v161 offset:19456
	ds_read_b128 v[224:227], v161 offset:20480
	ds_read_b128 v[228:231], v161 offset:21504
	ds_read_b128 v[232:235], v161 offset:22528
	ds_read_b128 v[236:239], v161 offset:23552
	global_load_lds_dwordx4 v[186:187], off
	s_add_i32 m0, s47, 0x2000
	s_add_u32 s76, s40, 0x80000
	v_lshl_add_u64 v[240:241], s[40:41], 0, v[144:145]
	s_addc_u32 s77, s41, 0
	s_add_i32 s47, s80, s4
	global_load_lds_dwordx4 v[240:241], off
	v_lshl_add_u64 v[242:243], s[76:77], 0, v[148:149]
	s_mov_b32 m0, s47
	v_lshl_add_u64 v[244:245], s[58:59], 0, v[146:147]
	global_load_lds_dwordx4 v[242:243], off
	v_lshl_add_u64 v[242:243], s[76:77], 0, v[144:145]
	s_add_i32 m0, s47, 0x2000
	s_nop 0
	global_load_lds_dwordx4 v[242:243], off
	v_lshl_add_u64 v[242:243], s[58:59], 0, v[150:151]
	s_mov_b32 m0, s5
	s_nop 0
	global_load_lds_dwordx4 v[242:243], off
	s_mov_b32 m0, s30
	s_nop 0
	global_load_lds_dwordx4 v[244:245], off
	s_waitcnt vmcnt(8)
	s_waitcnt lgkmcnt(0)
	s_barrier
; #define PG8_STAGE(bufoff, gbase, voff) do { _Pragma("unroll") for (int _i = 0; _i < 2; ++_i) \
;         __builtin_amdgcn_global_load_lds((const unsigned*)((const char*)(gbase) + (voff)[_i]), (PG8_LAS unsigned*)(lds + (bufoff) + ldsw + _i * 8192), 16, 0, 0); } while (0)
; #define PG8_LDA(dst, b, h) do { _Pragma("unroll") for (int m = 0; m < 4; ++m) _Pragma("unroll") for (int k = 0; k < 2; ++k) dst[m][k] = *(const PG8_LAS bf16x8*)(lds + PG8_SA(b, h) + aoff + m * 2048 + k * 1024); } while (0)
; #define PG8_LDB(dst, b, h) do { _Pragma("unroll") for (int n = 0; n < 2; ++n) _Pragma("unroll") for (int k = 0; k < 2; ++k) dst[n][k] = *(const PG8_LAS bf16x8*)(lds + PG8_SB(b, h) + boff + n * 2048 + k * 1024); } while (0)
; #define PG8_MMA(ai, bj, At, Bt) do { __builtin_amdgcn_s_setprio(1); _Pragma("unroll") for (int m = 0; m < 4; ++m) _Pragma("unroll") for (int n = 0; n < 2; ++n) _Pragma("unroll") for (int k = 0; k < 2; ++k) \
;         acc[ai][bj][m][n] = __builtin_amdgcn_mfma_f32_16x16x32_bf16(Bt[n][k], At[m][k], acc[ai][bj][m][n], 0, 0, 0); __builtin_amdgcn_s_setprio(0); } while (0)
; #define PG8_WAIT_V(n) asm volatile("s_waitcnt vmcnt(" #n ")" ::: "memory")
; #define PG8_WAIT_L(n) asm volatile("s_waitcnt lgkmcnt(" #n ")" ::: "memory")
; #define PG8_BAR __builtin_amdgcn_s_barrier()
; #define PG8_SCHED __builtin_amdgcn_sched_barrier(0)
; template <class Epi, class Sched, bool ALIGN_EPI = false, bool SP2 = false>
; __device__ __forceinline__ void gemm_phase(PG8_LAS unsigned char* lds, const Gemm g, const Sched& S, const Epi& E) {
;     ...
;             PG8_WAIT_V(8); PG8_WAIT_L(0); PG8_BAR; PG8_MMA(1, 0, At, B0); PG8_MMA(1, 1, At, B1); PG8_BAR; PG8_SCHED;
;             PG8_LDB(B0, 1, 0); PG8_LDB(B1, 1, 1); PG8_SCHED; PG8_LDA(At, 1, 0); PG8_STAGE(PG8_SA(0, 1), a2 + hstep, voffA);
;             PG8_WAIT_V(8); PG8_WAIT_L(0); PG8_BAR; PG8_MMA(0, 0, At, B0); PG8_MMA(0, 1, At, B1); PG8_BAR; PG8_SCHED;
;             PG8_LDA(At, 1, 1); PG8_STAGE(PG8_SB(1, 0), b3, voffB); PG8_STAGE(PG8_SB(1, 1), b3 + hstep, voffB); PG8_STAGE(PG8_SA(1, 0), a3, voffA);
;             PG8_WAIT_V(8); PG8_WAIT_L(0); PG8_BAR; PG8_MMA(1, 0, At, B0); PG8_MMA(1, 1, At, B1); PG8_BAR; PG8_SCHED;
	s_setprio 1
	v_mfma_f32_16x16x32_bf16 v[62:65], v[156:159], v[208:211], v[62:65]
	v_mfma_f32_16x16x32_bf16 v[58:61], v[166:169], v[208:211], v[58:61]
	v_mfma_f32_16x16x32_bf16 v[46:49], v[156:159], v[216:219], v[46:49]
	v_mfma_f32_16x16x32_bf16 v[42:45], v[166:169], v[216:219], v[42:45]
	v_mfma_f32_16x16x32_bf16 v[30:33], v[156:159], v[224:227], v[30:33]
	v_mfma_f32_16x16x32_bf16 v[26:29], v[166:169], v[224:227], v[26:29]
	v_mfma_f32_16x16x32_bf16 v[14:17], v[156:159], v[232:235], v[14:17]
	v_mfma_f32_16x16x32_bf16 v[10:13], v[166:169], v[232:235], v[10:13]
	s_setprio 0
	s_setprio 1
	v_mfma_f32_16x16x32_bf16 v[62:65], v[162:165], v[212:215], v[62:65]
	v_mfma_f32_16x16x32_bf16 v[58:61], v[170:173], v[212:215], v[58:61]
	v_mfma_f32_16x16x32_bf16 v[46:49], v[162:165], v[220:223], v[46:49]
	v_mfma_f32_16x16x32_bf16 v[42:45], v[170:173], v[220:223], v[42:45]
	v_mfma_f32_16x16x32_bf16 v[30:33], v[162:165], v[228:231], v[30:33]
	v_mfma_f32_16x16x32_bf16 v[26:29], v[170:173], v[228:231], v[26:29]
	v_mfma_f32_16x16x32_bf16 v[14:17], v[162:165], v[236:239], v[14:17]
	v_mfma_f32_16x16x32_bf16 v[10:13], v[170:173], v[236:239], v[10:13]
	s_setprio 0
	s_setprio 1
	v_mfma_f32_16x16x32_bf16 v[54:57], v[174:177], v[208:211], v[54:57]
	v_mfma_f32_16x16x32_bf16 v[50:53], v[182:185], v[208:211], v[50:53]
	v_mfma_f32_16x16x32_bf16 v[38:41], v[174:177], v[216:219], v[38:41]
	v_mfma_f32_16x16x32_bf16 v[34:37], v[182:185], v[216:219], v[34:37]
	v_mfma_f32_16x16x32_bf16 v[22:25], v[174:177], v[224:227], v[22:25]
	v_mfma_f32_16x16x32_bf16 v[18:21], v[182:185], v[224:227], v[18:21]
	v_mfma_f32_16x16x32_bf16 v[6:9], v[174:177], v[232:235], v[6:9]
	v_mfma_f32_16x16x32_bf16 v[2:5], v[182:185], v[232:235], v[2:5]
	s_setprio 0
	s_setprio 1
	v_mfma_f32_16x16x32_bf16 v[54:57], v[178:181], v[212:215], v[54:57]
	v_mfma_f32_16x16x32_bf16 v[50:53], v[204:207], v[212:215], v[50:53]
	v_mfma_f32_16x16x32_bf16 v[38:41], v[178:181], v[220:223], v[38:41]
	v_mfma_f32_16x16x32_bf16 v[34:37], v[204:207], v[220:223], v[34:37]
	v_mfma_f32_16x16x32_bf16 v[22:25], v[178:181], v[228:231], v[22:25]
	v_mfma_f32_16x16x32_bf16 v[18:21], v[204:207], v[228:231], v[18:21]
	v_mfma_f32_16x16x32_bf16 v[6:9], v[178:181], v[236:239], v[6:9]
	v_mfma_f32_16x16x32_bf16 v[2:5], v[204:207], v[236:239], v[2:5]
	s_setprio 0
	s_barrier
	s_add_i32 s47, 0, 0x18000
	s_add_i32 s76, 0, 0x1c000
	v_add_u32_e32 v170, s47, v143
	v_add_u32_e32 v203, s76, v143
	ds_read_b128 v[156:159], v170
	ds_read_b128 v[162:165], v170 offset:1024
	ds_read_b128 v[166:169], v170 offset:2048
	ds_read_b128 v[170:173], v170 offset:3072
	ds_read_b128 v[174:177], v203
	ds_read_b128 v[178:181], v203 offset:1024
	ds_read_b128 v[182:185], v203 offset:2048
	ds_read_b128 v[204:207], v203 offset:3072
	s_add_u32 s58, s58, 0x80000
	s_addc_u32 s59, s59, 0
	s_mov_b32 m0, s34
	v_lshl_add_u64 v[246:247], s[58:59], 0, v[150:151]
	ds_read_b128 v[208:211], v161 offset:32768
	ds_read_b128 v[212:215], v161 offset:33792
	ds_read_b128 v[216:219], v161 offset:34816
	ds_read_b128 v[220:223], v161 offset:35840
	ds_read_b128 v[224:227], v161 offset:36864
	ds_read_b128 v[228:231], v161 offset:37888
	ds_read_b128 v[232:235], v161 offset:38912
	ds_read_b128 v[236:239], v161 offset:39936
	global_load_lds_dwordx4 v[246:247], off
	v_lshl_add_u64 v[246:247], s[58:59], 0, v[146:147]
	s_mov_b32 m0, s57
	s_nop 0
	global_load_lds_dwordx4 v[246:247], off
	s_waitcnt vmcnt(8)
	s_waitcnt lgkmcnt(0)
	s_barrier
	s_setprio 1
	v_mfma_f32_16x16x32_bf16 v[126:129], v[156:159], v[208:211], v[126:129]
	v_mfma_f32_16x16x32_bf16 v[122:125], v[166:169], v[208:211], v[122:125]
	v_mfma_f32_16x16x32_bf16 v[110:113], v[156:159], v[216:219], v[110:113]
	v_mfma_f32_16x16x32_bf16 v[106:109], v[166:169], v[216:219], v[106:109]
	v_mfma_f32_16x16x32_bf16 v[94:97], v[156:159], v[224:227], v[94:97]
	v_mfma_f32_16x16x32_bf16 v[90:93], v[166:169], v[224:227], v[90:93]
	v_mfma_f32_16x16x32_bf16 v[78:81], v[156:159], v[232:235], v[78:81]
	v_mfma_f32_16x16x32_bf16 v[74:77], v[166:169], v[232:235], v[74:77]
	s_setprio 0
	s_setprio 1
	v_mfma_f32_16x16x32_bf16 v[126:129], v[162:165], v[212:215], v[126:129]
	v_mfma_f32_16x16x32_bf16 v[122:125], v[170:173], v[212:215], v[122:125]
	v_mfma_f32_16x16x32_bf16 v[110:113], v[162:165], v[220:223], v[110:113]
	v_mfma_f32_16x16x32_bf16 v[106:109], v[170:173], v[220:223], v[106:109]
	v_mfma_f32_16x16x32_bf16 v[94:97], v[162:165], v[228:231], v[94:97]
	v_mfma_f32_16x16x32_bf16 v[90:93], v[170:173], v[228:231], v[90:93]
	v_mfma_f32_16x16x32_bf16 v[78:81], v[162:165], v[236:239], v[78:81]
	v_mfma_f32_16x16x32_bf16 v[74:77], v[170:173], v[236:239], v[74:77]
	s_setprio 0
	s_setprio 1
	v_mfma_f32_16x16x32_bf16 v[118:121], v[174:177], v[208:211], v[118:121]
	v_mfma_f32_16x16x32_bf16 v[114:117], v[182:185], v[208:211], v[114:117]
	v_mfma_f32_16x16x32_bf16 v[102:105], v[174:177], v[216:219], v[102:105]
	v_mfma_f32_16x16x32_bf16 v[98:101], v[182:185], v[216:219], v[98:101]
	v_mfma_f32_16x16x32_bf16 v[86:89], v[174:177], v[224:227], v[86:89]
	v_mfma_f32_16x16x32_bf16 v[82:85], v[182:185], v[224:227], v[82:85]
	v_mfma_f32_16x16x32_bf16 v[70:73], v[174:177], v[232:235], v[70:73]
	v_mfma_f32_16x16x32_bf16 v[66:69], v[182:185], v[232:235], v[66:69]
	s_setprio 0
	s_setprio 1
	v_mfma_f32_16x16x32_bf16 v[118:121], v[178:181], v[212:215], v[118:121]
	v_mfma_f32_16x16x32_bf16 v[114:117], v[204:207], v[212:215], v[114:117]
	v_mfma_f32_16x16x32_bf16 v[102:105], v[178:181], v[220:223], v[102:105]
	v_mfma_f32_16x16x32_bf16 v[98:101], v[204:207], v[220:223], v[98:101]
	v_mfma_f32_16x16x32_bf16 v[86:89], v[178:181], v[228:231], v[86:89]
	v_mfma_f32_16x16x32_bf16 v[82:85], v[204:207], v[228:231], v[82:85]
	v_mfma_f32_16x16x32_bf16 v[70:73], v[178:181], v[236:239], v[70:73]
	v_mfma_f32_16x16x32_bf16 v[66:69], v[204:207], v[236:239], v[66:69]
	s_setprio 0
	s_barrier
; #define PG8_STAGE(bufoff, gbase, voff) do { _Pragma("unroll") for (int _i = 0; _i < 2; ++_i) \
;         __builtin_amdgcn_global_load_lds((const unsigned*)((const char*)(gbase) + (voff)[_i]), (PG8_LAS unsigned*)(lds + (bufoff) + ldsw + _i * 8192), 16, 0, 0); } while (0)
; #define PG8_LDA(dst, b, h) do { _Pragma("unroll") for (int m = 0; m < 4; ++m) _Pragma("unroll") for (int k = 0; k < 2; ++k) dst[m][k] = *(const PG8_LAS bf16x8*)(lds + PG8_SA(b, h) + aoff + m * 2048 + k * 1024); } while (0)
; #define PG8_MMA(ai, bj, At, Bt) do { __builtin_amdgcn_s_setprio(1); _Pragma("unroll") for (int m = 0; m < 4; ++m) _Pragma("unroll") for (int n = 0; n < 2; ++n) _Pragma("unroll") for (int k = 0; k < 2; ++k) \
;         acc[ai][bj][m][n] = __builtin_amdgcn_mfma_f32_16x16x32_bf16(Bt[n][k], At[m][k], acc[ai][bj][m][n], 0, 0, 0); __builtin_amdgcn_s_setprio(0); } while (0)
; #define PG8_WAIT_V(n) asm volatile("s_waitcnt vmcnt(" #n ")" ::: "memory")
; #define PG8_WAIT_L(n) asm volatile("s_waitcnt lgkmcnt(" #n ")" ::: "memory")
; #define PG8_BAR __builtin_amdgcn_s_barrier()
; #define PG8_SCHED __builtin_amdgcn_sched_barrier(0)
;     __device__ __forceinline__ void operator()(const f32x4 (&acc)[2][2][4][2], const Unit& u, int wr, int wc, int fr, int fq) const {
;     ...
;             for (int m = 0; m < 4; ++m) { const size_t row = (size_t)(row0 + ai * HALF + m * 16); float ss = 0.f;
; #pragma unroll
;                 for (int bj = 0; bj < 2; ++bj) { const size_t off = row * DM + col0 + bj * HALF;
;                     f32x4 v0 = acc[ai][bj][m][0] + *(const f32x4*)(base + off), v1 = acc[ai][bj][m][1] + *(const f32x4*)(base + off + 4);
; template <class Epi, class Sched, bool ALIGN_EPI = false, bool SP2 = false>
; __device__ __forceinline__ void gemm_phase(PG8_LAS unsigned char* lds, const Gemm g, const Sched& S, const Epi& E) {
;     ...
;             PG8_LDA(At, 1, 1); PG8_STAGE(PG8_SB(1, 0), b3, voffB); PG8_STAGE(PG8_SB(1, 1), b3 + hstep, voffB); PG8_STAGE(PG8_SA(1, 0), a3, voffA);
;             PG8_WAIT_V(8); PG8_WAIT_L(0); PG8_BAR; PG8_MMA(1, 0, At, B0); PG8_MMA(1, 1, At, B1); PG8_BAR; PG8_SCHED;
	s_add_i32 s47, s47, s4
	v_lshl_add_u64 v[186:187], v[186:187], 0, s[68:69]
	s_mov_b32 m0, s47
	ds_read_b128 v[208:211], v161 offset:49152
	ds_read_b128 v[212:215], v161 offset:50176
	ds_read_b128 v[216:219], v161 offset:51200
	ds_read_b128 v[220:223], v161 offset:52224
	ds_read_b128 v[224:227], v161 offset:53248
	ds_read_b128 v[228:231], v161 offset:54272
	ds_read_b128 v[232:235], v161 offset:55296
	ds_read_b128 v[236:239], v161 offset:56320
	global_load_lds_dwordx4 v[186:187], off
	s_add_i32 m0, s47, 0x2000
	s_add_u32 s40, s40, 0x80080
	v_lshl_add_u64 v[186:187], v[240:241], 0, s[68:69]
	s_addc_u32 s41, s41, 0
	s_add_i32 s47, s76, s4
	global_load_lds_dwordx4 v[186:187], off
	v_lshl_add_u64 v[186:187], s[40:41], 0, v[148:149]
	s_mov_b32 m0, s47
	s_nop 0
	global_load_lds_dwordx4 v[186:187], off
	v_lshl_add_u64 v[186:187], s[40:41], 0, v[144:145]
	s_add_i32 m0, s47, 0x2000
	s_nop 0
	global_load_lds_dwordx4 v[186:187], off
	v_lshl_add_u64 v[186:187], v[242:243], 0, s[68:69]
	s_mov_b32 m0, s67
	s_nop 0
	global_load_lds_dwordx4 v[186:187], off
	v_lshl_add_u64 v[186:187], v[244:245], 0, s[68:69]
	s_mov_b32 m0, s28
	s_nop 0
	global_load_lds_dwordx4 v[186:187], off
	s_nop 0
	s_waitcnt vmcnt(8)
	s_waitcnt lgkmcnt(0)
	s_barrier
	s_setprio 1
	v_mfma_f32_16x16x32_bf16 v[62:65], v[156:159], v[208:211], v[62:65]
	v_mfma_f32_16x16x32_bf16 v[58:61], v[166:169], v[208:211], v[58:61]
	v_mfma_f32_16x16x32_bf16 v[46:49], v[156:159], v[216:219], v[46:49]
	v_mfma_f32_16x16x32_bf16 v[42:45], v[166:169], v[216:219], v[42:45]
	v_mfma_f32_16x16x32_bf16 v[30:33], v[156:159], v[224:227], v[30:33]
	v_mfma_f32_16x16x32_bf16 v[26:29], v[166:169], v[224:227], v[26:29]
	v_mfma_f32_16x16x32_bf16 v[14:17], v[156:159], v[232:235], v[14:17]
	v_mfma_f32_16x16x32_bf16 v[10:13], v[166:169], v[232:235], v[10:13]
	s_setprio 0
	s_setprio 1
	v_mfma_f32_16x16x32_bf16 v[62:65], v[162:165], v[212:215], v[62:65]
	v_mfma_f32_16x16x32_bf16 v[58:61], v[170:173], v[212:215], v[58:61]
	v_mfma_f32_16x16x32_bf16 v[46:49], v[162:165], v[220:223], v[46:49]
	v_mfma_f32_16x16x32_bf16 v[42:45], v[170:173], v[220:223], v[42:45]
	v_mfma_f32_16x16x32_bf16 v[30:33], v[162:165], v[228:231], v[30:33]
	v_mfma_f32_16x16x32_bf16 v[26:29], v[170:173], v[228:231], v[26:29]
	v_mfma_f32_16x16x32_bf16 v[14:17], v[162:165], v[236:239], v[14:17]
	v_mfma_f32_16x16x32_bf16 v[10:13], v[170:173], v[236:239], v[10:13]
	s_setprio 0
	s_setprio 1
	v_mfma_f32_16x16x32_bf16 v[54:57], v[174:177], v[208:211], v[54:57]
	v_mfma_f32_16x16x32_bf16 v[50:53], v[182:185], v[208:211], v[50:53]
	v_mfma_f32_16x16x32_bf16 v[38:41], v[174:177], v[216:219], v[38:41]
	v_mfma_f32_16x16x32_bf16 v[34:37], v[182:185], v[216:219], v[34:37]
	v_mfma_f32_16x16x32_bf16 v[22:25], v[174:177], v[224:227], v[22:25]
	v_mfma_f32_16x16x32_bf16 v[18:21], v[182:185], v[224:227], v[18:21]
	v_mfma_f32_16x16x32_bf16 v[6:9], v[174:177], v[232:235], v[6:9]
	v_mfma_f32_16x16x32_bf16 v[2:5], v[182:185], v[232:235], v[2:5]
	s_setprio 0
	s_setprio 1
	v_mfma_f32_16x16x32_bf16 v[54:57], v[178:181], v[212:215], v[54:57]
	v_mfma_f32_16x16x32_bf16 v[50:53], v[204:207], v[212:215], v[50:53]
	v_mfma_f32_16x16x32_bf16 v[38:41], v[178:181], v[220:223], v[38:41]
	v_mfma_f32_16x16x32_bf16 v[34:37], v[204:207], v[220:223], v[34:37]
	v_mfma_f32_16x16x32_bf16 v[22:25], v[178:181], v[228:231], v[22:25]
	v_mfma_f32_16x16x32_bf16 v[18:21], v[204:207], v[228:231], v[18:21]
	v_mfma_f32_16x16x32_bf16 v[6:9], v[178:181], v[236:239], v[6:9]
	v_mfma_f32_16x16x32_bf16 v[2:5], v[204:207], v[236:239], v[2:5]
	s_setprio 0
	s_barrier
	s_add_i32 s46, s46, 2
	s_add_u32 vcc_lo, vcc_lo, 0x100
	s_addc_u32 vcc_hi, vcc_hi, 0
	s_add_u32 s78, s78, 0x100
	s_addc_u32 s79, s79, 0
	s_cmp_gt_u32 s46, 29
	s_cbranch_scc0 .LBB0_98
	v_lshl_add_u32 v156, s73, 8, v1
	v_lshl_or_b32 v157, s54, 8, v160
	v_lshl_add_u32 v157, v156, 11, v157
	v_mov_b32_e32 v247, 0
	v_lshlrev_b32_e32 v246, 2, v157
	v_lshl_add_u64 v[162:163], s[8:9], 0, v[246:247]
	v_lshlrev_b32_e32 v246, 1, v157
	v_lshl_add_u64 v[244:245], s[70:71], 0, v[246:247]
	s_mov_b32 s41, 0
	global_load_dwordx4 v[164:167], v[162:163], off
	global_load_dwordx4 v[168:171], v[162:163], off offset:16
	global_load_dwordx4 v[172:175], v[162:163], off offset:512
	global_load_dwordx4 v[176:179], v[162:163], off offset:528
	s_mov_b32 s40, 0x20000
	v_lshl_add_u64 v[246:247], v[162:163], 0, s[40:41]
	global_load_dwordx4 v[180:183], v[246:247], off
	global_load_dwordx4 v[184:187], v[246:247], off offset:16
	global_load_dwordx4 v[204:207], v[246:247], off offset:512
	global_load_dwordx4 v[208:211], v[246:247], off offset:528
	s_mov_b32 s40, 0x40000
	v_lshl_add_u64 v[246:247], v[162:163], 0, s[40:41]
	global_load_dwordx4 v[212:215], v[246:247], off
	global_load_dwordx4 v[216:219], v[246:247], off offset:16
	global_load_dwordx4 v[220:223], v[246:247], off offset:512
	global_load_dwordx4 v[224:227], v[246:247], off offset:528
	s_mov_b32 s40, 0x60000
	v_lshl_add_u64 v[246:247], v[162:163], 0, s[40:41]
	global_load_dwordx4 v[228:231], v[246:247], off
	global_load_dwordx4 v[232:235], v[246:247], off offset:16
	global_load_dwordx4 v[236:239], v[246:247], off offset:512
	global_load_dwordx4 v[240:243], v[246:247], off offset:528
	s_and_b64 vcc, exec, s[36:37]
	s_cbranch_vccz .Lx1_nobar
	s_barrier

; #define PG8_STAGE(bufoff, gbase, voff) do { _Pragma("unroll") for (int _i = 0; _i < 2; ++_i) \
;         __builtin_amdgcn_global_load_lds((const unsigned*)((const char*)(gbase) + (voff)[_i]), (PG8_LAS unsigned*)(lds + (bufoff) + ldsw + _i * 8192), 16, 0, 0); } while (0)
; #define PG8_LDA(dst, b, h) do { _Pragma("unroll") for (int m = 0; m < 4; ++m) _Pragma("unroll") for (int k = 0; k < 2; ++k) dst[m][k] = *(const PG8_LAS bf16x8*)(lds + PG8_SA(b, h) + aoff + m * 2048 + k * 1024); } while (0)
; #define PG8_LDB(dst, b, h) do { _Pragma("unroll") for (int n = 0; n < 2; ++n) _Pragma("unroll") for (int k = 0; k < 2; ++k) dst[n][k] = *(const PG8_LAS bf16x8*)(lds + PG8_SB(b, h) + boff + n * 2048 + k * 1024); } while (0)
; #define PG8_MMA(ai, bj, At, Bt) do { __builtin_amdgcn_s_setprio(1); _Pragma("unroll") for (int m = 0; m < 4; ++m) _Pragma("unroll") for (int n = 0; n < 2; ++n) _Pragma("unroll") for (int k = 0; k < 2; ++k) \
;         acc[ai][bj][m][n] = __builtin_amdgcn_mfma_f32_16x16x32_bf16(Bt[n][k], At[m][k], acc[ai][bj][m][n], 0, 0, 0); __builtin_amdgcn_s_setprio(0); } while (0)
; #define PG8_WAIT_V(n) asm volatile("s_waitcnt vmcnt(" #n ")" ::: "memory")
; #define PG8_WAIT_L(n) asm volatile("s_waitcnt lgkmcnt(" #n ")" ::: "memory")
; template <class Epi, class Sched, bool ALIGN_EPI = false, bool SP2 = false>
; __device__ __forceinline__ void gemm_phase(PG8_LAS unsigned char* lds, const Gemm g, const Sched& S, const Epi& E) {
;     ...
;             const bool last = (t == nt - 2);
;             const char* a1 = cA + (size_t)(t + 1) * kstep;
;             const char* a2 = last ? nA : cA + (size_t)(t + 2) * kstep; const char* b2 = last ? nB : cB + (size_t)(t + 2) * kstep;
;             const char* a3 = a2 + kstep; const char* b3 = b2 + kstep;
;             if (last && has_next) S.a_ready(nxt);
;             if constexpr (SP2) {
;             PG8_LDB(B0, 0, 0); PG8_LDB(B1, 0, 1); PG8_SCHED; PG8_LDA(At, 0, 0); PG8_STAGE(PG8_SA(1, 1), a1 + hstep, voffA);
;             PG8_WAIT_V(8); PG8_WAIT_L(0); PG8_BAR; PG8_MMA(0, 0, At, B0); PG8_MMA(0, 1, At, B1); PG8_BAR; PG8_SCHED;
;             PG8_LDA(At, 0, 1); PG8_STAGE(PG8_SB(0, 0), b2, voffB); PG8_STAGE(PG8_SB(0, 1), b2 + hstep, voffB); PG8_STAGE(PG8_SA(0, 0), a2, voffA);
;             PG8_WAIT_V(8); PG8_WAIT_L(0); PG8_BAR; PG8_MMA(1, 0, At, B0); PG8_MMA(1, 1, At, B1); PG8_BAR; PG8_SCHED;
.LBB0_136:
	s_add_u32 s18, s58, 0xfffe0080
	s_addc_u32 s19, s59, -1
	s_add_i32 s46, 0, 0x10000
	s_cmp_eq_u32 s79, 4
	s_cselect_b32 s63, s37, s19
	s_cselect_b32 s62, s73, s18
	s_cselect_b32 s19, s11, s78
	s_cselect_b32 s18, s84, s85
	s_add_i32 s76, 0, 0x14000
	v_add_u32_e32 v172, s46, v1
	v_add_u32_e32 v203, s76, v1
	ds_read_b128 v[160:163], v172
	ds_read_b128 v[164:167], v172 offset:1024
	ds_read_b128 v[168:171], v172 offset:2048
	ds_read_b128 v[172:175], v172 offset:3072
	ds_read_b128 v[176:179], v203
	ds_read_b128 v[180:183], v203 offset:1024
	ds_read_b128 v[184:187], v203 offset:2048
	ds_read_b128 v[204:207], v203 offset:3072
	v_lshl_add_u64 v[240:241], s[58:59], 0, v[156:157]
	s_add_i32 m0, s5, 0xc000
	ds_read_b128 v[208:211], v143
	ds_read_b128 v[212:215], v143 offset:1024
	ds_read_b128 v[216:219], v143 offset:2048
	ds_read_b128 v[220:223], v143 offset:3072
	ds_read_b128 v[224:227], v143 offset:4096
	ds_read_b128 v[228:231], v143 offset:5120
	ds_read_b128 v[232:235], v143 offset:6144
	ds_read_b128 v[236:239], v143 offset:7168
	global_load_lds_dwordx4 v[240:241], off
	v_lshl_add_u64 v[240:241], s[58:59], 0, v[158:159]
	s_add_i32 m0, s5, 0xe000
	s_nop 0
	global_load_lds_dwordx4 v[240:241], off
	s_nop 0
	s_waitcnt vmcnt(8)
	s_waitcnt lgkmcnt(0)
	s_barrier
	s_setprio 1
	v_mfma_f32_16x16x32_bf16 v[126:129], v[160:163], v[208:211], v[126:129]
	v_mfma_f32_16x16x32_bf16 v[122:125], v[168:171], v[208:211], v[122:125]
	v_mfma_f32_16x16x32_bf16 v[110:113], v[160:163], v[216:219], v[110:113]
	v_mfma_f32_16x16x32_bf16 v[106:109], v[168:171], v[216:219], v[106:109]
	v_mfma_f32_16x16x32_bf16 v[94:97], v[160:163], v[224:227], v[94:97]
	v_mfma_f32_16x16x32_bf16 v[90:93], v[168:171], v[224:227], v[90:93]
	v_mfma_f32_16x16x32_bf16 v[78:81], v[160:163], v[232:235], v[78:81]
	v_mfma_f32_16x16x32_bf16 v[74:77], v[168:171], v[232:235], v[74:77]
	s_setprio 0
	s_setprio 1
	v_mfma_f32_16x16x32_bf16 v[126:129], v[164:167], v[212:215], v[126:129]
	v_mfma_f32_16x16x32_bf16 v[122:125], v[172:175], v[212:215], v[122:125]
	v_mfma_f32_16x16x32_bf16 v[110:113], v[164:167], v[220:223], v[110:113]
	v_mfma_f32_16x16x32_bf16 v[106:109], v[172:175], v[220:223], v[106:109]
	v_mfma_f32_16x16x32_bf16 v[94:97], v[164:167], v[228:231], v[94:97]
	v_mfma_f32_16x16x32_bf16 v[90:93], v[172:175], v[228:231], v[90:93]
	v_mfma_f32_16x16x32_bf16 v[78:81], v[164:167], v[236:239], v[78:81]
	v_mfma_f32_16x16x32_bf16 v[74:77], v[172:175], v[236:239], v[74:77]
	s_setprio 0
	s_setprio 1
	v_mfma_f32_16x16x32_bf16 v[118:121], v[176:179], v[208:211], v[118:121]
	v_mfma_f32_16x16x32_bf16 v[114:117], v[184:187], v[208:211], v[114:117]
	v_mfma_f32_16x16x32_bf16 v[102:105], v[176:179], v[216:219], v[102:105]
	v_mfma_f32_16x16x32_bf16 v[98:101], v[184:187], v[216:219], v[98:101]
	v_mfma_f32_16x16x32_bf16 v[86:89], v[176:179], v[224:227], v[86:89]
	v_mfma_f32_16x16x32_bf16 v[82:85], v[184:187], v[224:227], v[82:85]
	v_mfma_f32_16x16x32_bf16 v[70:73], v[176:179], v[232:235], v[70:73]
	v_mfma_f32_16x16x32_bf16 v[66:69], v[184:187], v[232:235], v[66:69]
	s_setprio 0
	s_setprio 1
	v_mfma_f32_16x16x32_bf16 v[118:121], v[180:183], v[212:215], v[118:121]
	v_mfma_f32_16x16x32_bf16 v[114:117], v[204:207], v[212:215], v[114:117]
	v_mfma_f32_16x16x32_bf16 v[102:105], v[180:183], v[220:223], v[102:105]
	v_mfma_f32_16x16x32_bf16 v[98:101], v[204:207], v[220:223], v[98:101]
	v_mfma_f32_16x16x32_bf16 v[86:89], v[180:183], v[228:231], v[86:89]
	v_mfma_f32_16x16x32_bf16 v[82:85], v[204:207], v[228:231], v[82:85]
	v_mfma_f32_16x16x32_bf16 v[70:73], v[180:183], v[236:239], v[70:73]
	v_mfma_f32_16x16x32_bf16 v[66:69], v[204:207], v[236:239], v[66:69]
	s_setprio 0
	s_barrier
	s_add_i32 s46, s46, s4
	v_lshl_add_u64 v[240:241], s[18:19], 0, v[148:149]
	s_mov_b32 m0, s46
	ds_read_b128 v[208:211], v143 offset:16384
	ds_read_b128 v[212:215], v143 offset:17408
	ds_read_b128 v[216:219], v143 offset:18432
	ds_read_b128 v[220:223], v143 offset:19456
	ds_read_b128 v[224:227], v143 offset:20480
	ds_read_b128 v[228:231], v143 offset:21504
	ds_read_b128 v[232:235], v143 offset:22528
	ds_read_b128 v[236:239], v143 offset:23552
	global_load_lds_dwordx4 v[240:241], off
	s_add_i32 m0, s46, 0x2000
	s_add_u32 s46, s18, 0x20000
	v_lshl_add_u64 v[242:243], s[18:19], 0, v[144:145]
	s_addc_u32 s47, s19, 0
	s_add_i32 s76, s76, s4
	global_load_lds_dwordx4 v[242:243], off
	v_lshl_add_u64 v[244:245], s[46:47], 0, v[148:149]
	s_mov_b32 m0, s76
	v_lshl_add_u64 v[246:247], s[62:63], 0, v[146:147]
	global_load_lds_dwordx4 v[244:245], off
	v_lshl_add_u64 v[244:245], s[46:47], 0, v[144:145]
	s_add_i32 m0, s76, 0x2000
	s_nop 0
	global_load_lds_dwordx4 v[244:245], off
	v_lshl_add_u64 v[244:245], s[62:63], 0, v[150:151]
	s_mov_b32 m0, s5
	s_nop 0
	global_load_lds_dwordx4 v[244:245], off
	s_mov_b32 m0, s28
	s_nop 0
	global_load_lds_dwordx4 v[246:247], off
	s_waitcnt vmcnt(8)
	s_waitcnt lgkmcnt(0)
	s_barrier
; #define PG8_STAGE(bufoff, gbase, voff) do { _Pragma("unroll") for (int _i = 0; _i < 2; ++_i) \
;         __builtin_amdgcn_global_load_lds((const unsigned*)((const char*)(gbase) + (voff)[_i]), (PG8_LAS unsigned*)(lds + (bufoff) + ldsw + _i * 8192), 16, 0, 0); } while (0)
; #define PG8_LDA(dst, b, h) do { _Pragma("unroll") for (int m = 0; m < 4; ++m) _Pragma("unroll") for (int k = 0; k < 2; ++k) dst[m][k] = *(const PG8_LAS bf16x8*)(lds + PG8_SA(b, h) + aoff + m * 2048 + k * 1024); } while (0)
; #define PG8_LDB(dst, b, h) do { _Pragma("unroll") for (int n = 0; n < 2; ++n) _Pragma("unroll") for (int k = 0; k < 2; ++k) dst[n][k] = *(const PG8_LAS bf16x8*)(lds + PG8_SB(b, h) + boff + n * 2048 + k * 1024); } while (0)
; #define PG8_MMA(ai, bj, At, Bt) do { __builtin_amdgcn_s_setprio(1); _Pragma("unroll") for (int m = 0; m < 4; ++m) _Pragma("unroll") for (int n = 0; n < 2; ++n) _Pragma("unroll") for (int k = 0; k < 2; ++k) \
;         acc[ai][bj][m][n] = __builtin_amdgcn_mfma_f32_16x16x32_bf16(Bt[n][k], At[m][k], acc[ai][bj][m][n], 0, 0, 0); __builtin_amdgcn_s_setprio(0); } while (0)
; #define PG8_WAIT_V(n) asm volatile("s_waitcnt vmcnt(" #n ")" ::: "memory")
; #define PG8_WAIT_L(n) asm volatile("s_waitcnt lgkmcnt(" #n ")" ::: "memory")
; #define PG8_BAR __builtin_amdgcn_s_barrier()
; #define PG8_SCHED __builtin_amdgcn_sched_barrier(0)
; template <class Epi, class Sched, bool ALIGN_EPI = false, bool SP2 = false>
; __device__ __forceinline__ void gemm_phase(PG8_LAS unsigned char* lds, const Gemm g, const Sched& S, const Epi& E) {
;     ...
;             PG8_WAIT_V(8); PG8_WAIT_L(0); PG8_BAR; PG8_MMA(1, 0, At, B0); PG8_MMA(1, 1, At, B1); PG8_BAR; PG8_SCHED;
;             PG8_LDB(B0, 1, 0); PG8_LDB(B1, 1, 1); PG8_SCHED; PG8_LDA(At, 1, 0); PG8_STAGE(PG8_SA(0, 1), a2 + hstep, voffA);
;             PG8_WAIT_V(8); PG8_WAIT_L(0); PG8_BAR; PG8_MMA(0, 0, At, B0); PG8_MMA(0, 1, At, B1); PG8_BAR; PG8_SCHED;
;             PG8_LDA(At, 1, 1); PG8_STAGE(PG8_SB(1, 0), b3, voffB); PG8_STAGE(PG8_SB(1, 1), b3 + hstep, voffB); PG8_STAGE(PG8_SA(1, 0), a3, voffA);
;             PG8_WAIT_V(8); PG8_WAIT_L(0); PG8_BAR; PG8_MMA(1, 0, At, B0); PG8_MMA(1, 1, At, B1); PG8_BAR; PG8_SCHED;
	s_setprio 1
	v_mfma_f32_16x16x32_bf16 v[62:65], v[160:163], v[208:211], v[62:65]
	v_mfma_f32_16x16x32_bf16 v[58:61], v[168:171], v[208:211], v[58:61]
	v_mfma_f32_16x16x32_bf16 v[46:49], v[160:163], v[216:219], v[46:49]
	v_mfma_f32_16x16x32_bf16 v[42:45], v[168:171], v[216:219], v[42:45]
	v_mfma_f32_16x16x32_bf16 v[30:33], v[160:163], v[224:227], v[30:33]
	v_mfma_f32_16x16x32_bf16 v[26:29], v[168:171], v[224:227], v[26:29]
	v_mfma_f32_16x16x32_bf16 v[14:17], v[160:163], v[232:235], v[14:17]
	v_mfma_f32_16x16x32_bf16 v[10:13], v[168:171], v[232:235], v[10:13]
	s_setprio 0
	s_setprio 1
	v_mfma_f32_16x16x32_bf16 v[62:65], v[164:167], v[212:215], v[62:65]
	v_mfma_f32_16x16x32_bf16 v[58:61], v[172:175], v[212:215], v[58:61]
	v_mfma_f32_16x16x32_bf16 v[46:49], v[164:167], v[220:223], v[46:49]
	v_mfma_f32_16x16x32_bf16 v[42:45], v[172:175], v[220:223], v[42:45]
	v_mfma_f32_16x16x32_bf16 v[30:33], v[164:167], v[228:231], v[30:33]
	v_mfma_f32_16x16x32_bf16 v[26:29], v[172:175], v[228:231], v[26:29]
	v_mfma_f32_16x16x32_bf16 v[14:17], v[164:167], v[236:239], v[14:17]
	v_mfma_f32_16x16x32_bf16 v[10:13], v[172:175], v[236:239], v[10:13]
	s_setprio 0
	s_setprio 1
	v_mfma_f32_16x16x32_bf16 v[54:57], v[176:179], v[208:211], v[54:57]
	v_mfma_f32_16x16x32_bf16 v[50:53], v[184:187], v[208:211], v[50:53]
	v_mfma_f32_16x16x32_bf16 v[38:41], v[176:179], v[216:219], v[38:41]
	v_mfma_f32_16x16x32_bf16 v[34:37], v[184:187], v[216:219], v[34:37]
	v_mfma_f32_16x16x32_bf16 v[22:25], v[176:179], v[224:227], v[22:25]
	v_mfma_f32_16x16x32_bf16 v[18:21], v[184:187], v[224:227], v[18:21]
	v_mfma_f32_16x16x32_bf16 v[6:9], v[176:179], v[232:235], v[6:9]
	v_mfma_f32_16x16x32_bf16 v[2:5], v[184:187], v[232:235], v[2:5]
	s_setprio 0
	s_setprio 1
	v_mfma_f32_16x16x32_bf16 v[54:57], v[180:183], v[212:215], v[54:57]
	v_mfma_f32_16x16x32_bf16 v[50:53], v[204:207], v[212:215], v[50:53]
	v_mfma_f32_16x16x32_bf16 v[38:41], v[180:183], v[220:223], v[38:41]
	v_mfma_f32_16x16x32_bf16 v[34:37], v[204:207], v[220:223], v[34:37]
	v_mfma_f32_16x16x32_bf16 v[22:25], v[180:183], v[228:231], v[22:25]
	v_mfma_f32_16x16x32_bf16 v[18:21], v[204:207], v[228:231], v[18:21]
	v_mfma_f32_16x16x32_bf16 v[6:9], v[180:183], v[236:239], v[6:9]
	v_mfma_f32_16x16x32_bf16 v[2:5], v[204:207], v[236:239], v[2:5]
	s_setprio 0
	s_barrier
	s_add_i32 s76, 0, 0x18000
	s_add_i32 s77, 0, 0x1c000
	v_add_u32_e32 v172, s76, v1
	v_add_u32_e32 v203, s77, v1
	ds_read_b128 v[160:163], v172
	ds_read_b128 v[164:167], v172 offset:1024
	ds_read_b128 v[168:171], v172 offset:2048
	ds_read_b128 v[172:175], v172 offset:3072
	ds_read_b128 v[176:179], v203
	ds_read_b128 v[180:183], v203 offset:1024
	ds_read_b128 v[184:187], v203 offset:2048
	ds_read_b128 v[204:207], v203 offset:3072
	s_add_u32 s46, s62, 0x20000
	s_addc_u32 s47, s63, 0
	s_mov_b32 m0, s30
	v_lshl_add_u64 v[248:249], s[46:47], 0, v[150:151]
	ds_read_b128 v[208:211], v143 offset:32768
	ds_read_b128 v[212:215], v143 offset:33792
	ds_read_b128 v[216:219], v143 offset:34816
	ds_read_b128 v[220:223], v143 offset:35840
	ds_read_b128 v[224:227], v143 offset:36864
	ds_read_b128 v[228:231], v143 offset:37888
	ds_read_b128 v[232:235], v143 offset:38912
	ds_read_b128 v[236:239], v143 offset:39936
	global_load_lds_dwordx4 v[248:249], off
	v_lshl_add_u64 v[248:249], s[46:47], 0, v[146:147]
	s_mov_b32 m0, s34
	s_nop 0
	global_load_lds_dwordx4 v[248:249], off
	s_waitcnt vmcnt(8)
	s_waitcnt lgkmcnt(0)
	s_barrier
	s_setprio 1
	v_mfma_f32_16x16x32_bf16 v[126:129], v[160:163], v[208:211], v[126:129]
	v_mfma_f32_16x16x32_bf16 v[122:125], v[168:171], v[208:211], v[122:125]
	v_mfma_f32_16x16x32_bf16 v[110:113], v[160:163], v[216:219], v[110:113]
	v_mfma_f32_16x16x32_bf16 v[106:109], v[168:171], v[216:219], v[106:109]
	v_mfma_f32_16x16x32_bf16 v[94:97], v[160:163], v[224:227], v[94:97]
	v_mfma_f32_16x16x32_bf16 v[90:93], v[168:171], v[224:227], v[90:93]
	v_mfma_f32_16x16x32_bf16 v[78:81], v[160:163], v[232:235], v[78:81]
	v_mfma_f32_16x16x32_bf16 v[74:77], v[168:171], v[232:235], v[74:77]
	s_setprio 0
	s_setprio 1
	v_mfma_f32_16x16x32_bf16 v[126:129], v[164:167], v[212:215], v[126:129]
	v_mfma_f32_16x16x32_bf16 v[122:125], v[172:175], v[212:215], v[122:125]
	v_mfma_f32_16x16x32_bf16 v[110:113], v[164:167], v[220:223], v[110:113]
	v_mfma_f32_16x16x32_bf16 v[106:109], v[172:175], v[220:223], v[106:109]
	v_mfma_f32_16x16x32_bf16 v[94:97], v[164:167], v[228:231], v[94:97]
	v_mfma_f32_16x16x32_bf16 v[90:93], v[172:175], v[228:231], v[90:93]
	v_mfma_f32_16x16x32_bf16 v[78:81], v[164:167], v[236:239], v[78:81]
	v_mfma_f32_16x16x32_bf16 v[74:77], v[172:175], v[236:239], v[74:77]
	s_setprio 0
	s_setprio 1
	v_mfma_f32_16x16x32_bf16 v[118:121], v[176:179], v[208:211], v[118:121]
	v_mfma_f32_16x16x32_bf16 v[114:117], v[184:187], v[208:211], v[114:117]
	v_mfma_f32_16x16x32_bf16 v[102:105], v[176:179], v[216:219], v[102:105]
	v_mfma_f32_16x16x32_bf16 v[98:101], v[184:187], v[216:219], v[98:101]
	v_mfma_f32_16x16x32_bf16 v[86:89], v[176:179], v[224:227], v[86:89]
	v_mfma_f32_16x16x32_bf16 v[82:85], v[184:187], v[224:227], v[82:85]
	v_mfma_f32_16x16x32_bf16 v[70:73], v[176:179], v[232:235], v[70:73]
	v_mfma_f32_16x16x32_bf16 v[66:69], v[184:187], v[232:235], v[66:69]
	s_setprio 0
	s_setprio 1
	v_mfma_f32_16x16x32_bf16 v[118:121], v[180:183], v[212:215], v[118:121]
	v_mfma_f32_16x16x32_bf16 v[114:117], v[204:207], v[212:215], v[114:117]
	v_mfma_f32_16x16x32_bf16 v[102:105], v[180:183], v[220:223], v[102:105]
	v_mfma_f32_16x16x32_bf16 v[98:101], v[204:207], v[220:223], v[98:101]
	v_mfma_f32_16x16x32_bf16 v[86:89], v[180:183], v[228:231], v[86:89]
	v_mfma_f32_16x16x32_bf16 v[82:85], v[204:207], v[228:231], v[82:85]
	v_mfma_f32_16x16x32_bf16 v[70:73], v[180:183], v[236:239], v[70:73]
	v_mfma_f32_16x16x32_bf16 v[66:69], v[204:207], v[236:239], v[66:69]
	s_setprio 0
	s_barrier
; #define PG8_STAGE(bufoff, gbase, voff) do { _Pragma("unroll") for (int _i = 0; _i < 2; ++_i) \
;         __builtin_amdgcn_global_load_lds((const unsigned*)((const char*)(gbase) + (voff)[_i]), (PG8_LAS unsigned*)(lds + (bufoff) + ldsw + _i * 8192), 16, 0, 0); } while (0)
; #define PG8_LDA(dst, b, h) do { _Pragma("unroll") for (int m = 0; m < 4; ++m) _Pragma("unroll") for (int k = 0; k < 2; ++k) dst[m][k] = *(const PG8_LAS bf16x8*)(lds + PG8_SA(b, h) + aoff + m * 2048 + k * 1024); } while (0)
; #define PG8_MMA(ai, bj, At, Bt) do { __builtin_amdgcn_s_setprio(1); _Pragma("unroll") for (int m = 0; m < 4; ++m) _Pragma("unroll") for (int n = 0; n < 2; ++n) _Pragma("unroll") for (int k = 0; k < 2; ++k) \
;         acc[ai][bj][m][n] = __builtin_amdgcn_mfma_f32_16x16x32_bf16(Bt[n][k], At[m][k], acc[ai][bj][m][n], 0, 0, 0); __builtin_amdgcn_s_setprio(0); } while (0)
; #define PG8_WAIT_V(n) asm volatile("s_waitcnt vmcnt(" #n ")" ::: "memory")
; #define PG8_WAIT_L(n) asm volatile("s_waitcnt lgkmcnt(" #n ")" ::: "memory")
; #define PG8_BAR __builtin_amdgcn_s_barrier()
; #define PG8_SCHED __builtin_amdgcn_sched_barrier(0)
;     __device__ __forceinline__ void operator()(const f32x4 (&acc)[2][2][4][2], const Unit& u, int wr, int wc, int fr, int fq) const {
;         const int row0 = u.pm * BM + wr * 64 + fr, col0 = u.pn * BM + wc * 32 + 8 * fq;
;         const int tidn = (wr * 4 + wc) * 64 + fq * 16 + fr;
;         const u32x4* gp = (const u32x4*)G8 + (size_t)(u.pm * 16 + gsel + u.pn) * 8 * 512 + tidn;
;         u32x4* mp = M1 + (size_t)(u.pm * 8 + u.pn) * 16 * 512 + tidn;
;         constexpr float K255 = 1.0f / 255.0f;
; #pragma unroll
;         for (int ai = 0; ai < 2; ++ai)
; #pragma unroll
;             for (int m = 0; m < 4; ++m) { const size_t row = (size_t)(row0 + ai * HALF + m * 16);
;                 const u32x4 gw = gp[(ai * 4 + m) * 512];
; template <class Epi, class Sched, bool ALIGN_EPI = false, bool SP2 = false>
; __device__ __forceinline__ void gemm_phase(PG8_LAS unsigned char* lds, const Gemm g, const Sched& S, const Epi& E) {
;     ...
;             PG8_LDA(At, 1, 1); PG8_STAGE(PG8_SB(1, 0), b3, voffB); PG8_STAGE(PG8_SB(1, 1), b3 + hstep, voffB); PG8_STAGE(PG8_SA(1, 0), a3, voffA);
;             PG8_WAIT_V(8); PG8_WAIT_L(0); PG8_BAR; PG8_MMA(1, 0, At, B0); PG8_MMA(1, 1, At, B1); PG8_BAR; PG8_SCHED;
	s_add_i32 s46, s76, s4
	v_lshl_add_u64 v[240:241], v[240:241], 0, s[68:69]
	s_mov_b32 m0, s46
	ds_read_b128 v[208:211], v143 offset:49152
	ds_read_b128 v[212:215], v143 offset:50176
	ds_read_b128 v[216:219], v143 offset:51200
	ds_read_b128 v[220:223], v143 offset:52224
	ds_read_b128 v[224:227], v143 offset:53248
	ds_read_b128 v[228:231], v143 offset:54272
	ds_read_b128 v[232:235], v143 offset:55296
	ds_read_b128 v[236:239], v143 offset:56320
	global_load_lds_dwordx4 v[240:241], off
	s_add_i32 m0, s46, 0x2000
	s_add_u32 s18, s18, 0x20080
	v_lshl_add_u64 v[240:241], v[242:243], 0, s[68:69]
	s_addc_u32 s19, s19, 0
	s_add_i32 s46, s77, s4
	global_load_lds_dwordx4 v[240:241], off
	v_lshl_add_u64 v[240:241], s[18:19], 0, v[148:149]
	s_mov_b32 m0, s46
	s_nop 0
	global_load_lds_dwordx4 v[240:241], off
	v_lshl_add_u64 v[240:241], s[18:19], 0, v[144:145]
	s_add_i32 m0, s46, 0x2000
	s_nop 0
	global_load_lds_dwordx4 v[240:241], off
	v_lshl_add_u64 v[240:241], v[244:245], 0, s[68:69]
	s_mov_b32 m0, s54
	s_nop 0
	global_load_lds_dwordx4 v[240:241], off
	v_lshl_add_u64 v[240:241], v[246:247], 0, s[68:69]
	s_mov_b32 m0, s57
	s_nop 0
	global_load_lds_dwordx4 v[240:241], off
	s_nop 0
	s_waitcnt vmcnt(8)
	s_waitcnt lgkmcnt(0)
	s_barrier
	s_setprio 1
	v_mfma_f32_16x16x32_bf16 v[62:65], v[160:163], v[208:211], v[62:65]
	v_mfma_f32_16x16x32_bf16 v[58:61], v[168:171], v[208:211], v[58:61]
	v_mfma_f32_16x16x32_bf16 v[46:49], v[160:163], v[216:219], v[46:49]
	v_mfma_f32_16x16x32_bf16 v[42:45], v[168:171], v[216:219], v[42:45]
	v_mfma_f32_16x16x32_bf16 v[30:33], v[160:163], v[224:227], v[30:33]
	v_mfma_f32_16x16x32_bf16 v[26:29], v[168:171], v[224:227], v[26:29]
	v_mfma_f32_16x16x32_bf16 v[14:17], v[160:163], v[232:235], v[14:17]
	v_mfma_f32_16x16x32_bf16 v[10:13], v[168:171], v[232:235], v[10:13]
	s_setprio 0
	s_setprio 1
	v_mfma_f32_16x16x32_bf16 v[62:65], v[164:167], v[212:215], v[62:65]
	v_mfma_f32_16x16x32_bf16 v[58:61], v[172:175], v[212:215], v[58:61]
	v_mfma_f32_16x16x32_bf16 v[46:49], v[164:167], v[220:223], v[46:49]
	v_mfma_f32_16x16x32_bf16 v[42:45], v[172:175], v[220:223], v[42:45]
	v_mfma_f32_16x16x32_bf16 v[30:33], v[164:167], v[228:231], v[30:33]
	v_mfma_f32_16x16x32_bf16 v[26:29], v[172:175], v[228:231], v[26:29]
	v_mfma_f32_16x16x32_bf16 v[14:17], v[164:167], v[236:239], v[14:17]
	v_mfma_f32_16x16x32_bf16 v[10:13], v[172:175], v[236:239], v[10:13]
	s_setprio 0
	s_setprio 1
	v_mfma_f32_16x16x32_bf16 v[54:57], v[176:179], v[208:211], v[54:57]
	v_mfma_f32_16x16x32_bf16 v[50:53], v[184:187], v[208:211], v[50:53]
	v_mfma_f32_16x16x32_bf16 v[38:41], v[176:179], v[216:219], v[38:41]
	v_mfma_f32_16x16x32_bf16 v[34:37], v[184:187], v[216:219], v[34:37]
	v_mfma_f32_16x16x32_bf16 v[22:25], v[176:179], v[224:227], v[22:25]
	v_mfma_f32_16x16x32_bf16 v[18:21], v[184:187], v[224:227], v[18:21]
	v_mfma_f32_16x16x32_bf16 v[6:9], v[176:179], v[232:235], v[6:9]
	v_mfma_f32_16x16x32_bf16 v[2:5], v[184:187], v[232:235], v[2:5]
	s_setprio 0
	s_setprio 1
	v_mfma_f32_16x16x32_bf16 v[54:57], v[180:183], v[212:215], v[54:57]
	v_mfma_f32_16x16x32_bf16 v[50:53], v[204:207], v[212:215], v[50:53]
	v_mfma_f32_16x16x32_bf16 v[38:41], v[180:183], v[220:223], v[38:41]
	v_mfma_f32_16x16x32_bf16 v[34:37], v[204:207], v[220:223], v[34:37]
	v_mfma_f32_16x16x32_bf16 v[22:25], v[180:183], v[228:231], v[22:25]
	v_mfma_f32_16x16x32_bf16 v[18:21], v[204:207], v[228:231], v[18:21]
	v_mfma_f32_16x16x32_bf16 v[6:9], v[180:183], v[236:239], v[6:9]
	v_mfma_f32_16x16x32_bf16 v[2:5], v[204:207], v[236:239], v[2:5]
	s_setprio 0
	s_barrier
	s_add_i32 s79, s79, 2
	s_add_u32 s58, s58, 0x100
	s_addc_u32 s59, s59, 0
	s_add_u32 s85, s85, 0x100
	s_addc_u32 s78, s78, 0
	s_cmp_gt_u32 s79, 5
	s_cbranch_scc0 .LBB0_136
	s_lshl_b32 s11, s67, 4
	s_add_i32 s18, s11, s86
	s_ashr_i32 s19, s18, 31
	s_lshl_b64 s[46:47], s[18:19], 16
	v_lshl_add_u64 v[162:163], v[152:153], 0, s[46:47]
	s_lshl_b32 s11, s67, 3
	s_sub_i32 s18, s18, s11
	s_ashr_i32 s19, s18, 31
	s_lshl_b64 s[18:19], s[18:19], 17
	v_lshl_add_u64 v[160:161], v[154:155], 0, s[18:19]
	s_mov_b32 s47, 0
	global_load_dwordx4 v[168:171], v[162:163], off
	s_mov_b32 s46, 0x2000
	v_lshl_add_u64 v[164:165], v[162:163], 0, s[46:47]
	global_load_dwordx4 v[172:175], v[164:165], off
	s_mov_b32 s46, 0x4000
	v_lshl_add_u64 v[164:165], v[162:163], 0, s[46:47]
	global_load_dwordx4 v[176:179], v[164:165], off
	s_mov_b32 s46, 0x6000
	v_lshl_add_u64 v[164:165], v[162:163], 0, s[46:47]
	global_load_dwordx4 v[180:183], v[164:165], off
	s_mov_b32 s46, 0x8000
	v_lshl_add_u64 v[164:165], v[162:163], 0, s[46:47]
	global_load_dwordx4 v[184:187], v[164:165], off
	s_mov_b32 s46, 0xa000
	v_lshl_add_u64 v[164:165], v[162:163], 0, s[46:47]
	global_load_dwordx4 v[204:207], v[164:165], off
	s_mov_b32 s46, 0xc000
	v_lshl_add_u64 v[164:165], v[162:163], 0, s[46:47]
	global_load_dwordx4 v[208:211], v[164:165], off
	s_mov_b32 s46, 0xe000
	v_lshl_add_u64 v[164:165], v[162:163], 0, s[46:47]
	global_load_dwordx4 v[212:215], v[164:165], off
	s_and_b64 vcc, exec, s[8:9]
	s_cbranch_vccz .Lg0_nobar
	s_barrier

; #define PG8_STAGE(bufoff, gbase, voff) do { _Pragma("unroll") for (int _i = 0; _i < 2; ++_i) \
;         __builtin_amdgcn_global_load_lds((const unsigned*)((const char*)(gbase) + (voff)[_i]), (PG8_LAS unsigned*)(lds + (bufoff) + ldsw + _i * 8192), 16, 0, 0); } while (0)
; #define PG8_LDA(dst, b, h) do { _Pragma("unroll") for (int m = 0; m < 4; ++m) _Pragma("unroll") for (int k = 0; k < 2; ++k) dst[m][k] = *(const PG8_LAS bf16x8*)(lds + PG8_SA(b, h) + aoff + m * 2048 + k * 1024); } while (0)
; #define PG8_LDB(dst, b, h) do { _Pragma("unroll") for (int n = 0; n < 2; ++n) _Pragma("unroll") for (int k = 0; k < 2; ++k) dst[n][k] = *(const PG8_LAS bf16x8*)(lds + PG8_SB(b, h) + boff + n * 2048 + k * 1024); } while (0)
; #define PG8_MMA(ai, bj, At, Bt) do { __builtin_amdgcn_s_setprio(1); _Pragma("unroll") for (int m = 0; m < 4; ++m) _Pragma("unroll") for (int n = 0; n < 2; ++n) _Pragma("unroll") for (int k = 0; k < 2; ++k) \
;         acc[ai][bj][m][n] = __builtin_amdgcn_mfma_f32_16x16x32_bf16(Bt[n][k], At[m][k], acc[ai][bj][m][n], 0, 0, 0); __builtin_amdgcn_s_setprio(0); } while (0)
; #define PG8_WAIT_V(n) asm volatile("s_waitcnt vmcnt(" #n ")" ::: "memory")
; #define PG8_WAIT_L(n) asm volatile("s_waitcnt lgkmcnt(" #n ")" ::: "memory")
; template <class Epi, class Sched, bool ALIGN_EPI = false, bool SP2 = false>
; __device__ __forceinline__ void gemm_phase(PG8_LAS unsigned char* lds, const Gemm g, const Sched& S, const Epi& E) {
;     ...
;             const bool last = (t == nt - 2);
;             const char* a1 = cA + (size_t)(t + 1) * kstep;
;             const char* a2 = last ? nA : cA + (size_t)(t + 2) * kstep; const char* b2 = last ? nB : cB + (size_t)(t + 2) * kstep;
;             const char* a3 = a2 + kstep; const char* b3 = b2 + kstep;
;             if (last && has_next) S.a_ready(nxt);
;             if constexpr (SP2) {
;             PG8_LDB(B0, 0, 0); PG8_LDB(B1, 0, 1); PG8_SCHED; PG8_LDA(At, 0, 0); PG8_STAGE(PG8_SA(1, 1), a1 + hstep, voffA);
;             PG8_WAIT_V(8); PG8_WAIT_L(0); PG8_BAR; PG8_MMA(0, 0, At, B0); PG8_MMA(0, 1, At, B1); PG8_BAR; PG8_SCHED;
;             PG8_LDA(At, 0, 1); PG8_STAGE(PG8_SB(0, 0), b2, voffB); PG8_STAGE(PG8_SB(0, 1), b2 + hstep, voffB); PG8_STAGE(PG8_SA(0, 0), a2, voffA);
;             PG8_WAIT_V(8); PG8_WAIT_L(0); PG8_BAR; PG8_MMA(1, 0, At, B0); PG8_MMA(1, 1, At, B1); PG8_BAR; PG8_SCHED;
.LBB0_160:
	s_add_u32 s42, s36, 0x100
	s_addc_u32 s43, s37, 0
	s_add_i32 s47, 0, 0x10000
	s_cmp_eq_u32 s46, 20
	s_cselect_b32 s45, s1, s43
	s_cselect_b32 s44, s0, s42
	s_cselect_b32 s19, s7, s73
	s_cselect_b32 s18, s6, s60
	s_add_i32 s76, 0, 0x14000
	v_add_u32_e32 v174, s47, v143
	v_add_u32_e32 v186, s76, v143
	ds_read_b128 v[160:163], v174
	ds_read_b128 v[164:167], v174 offset:1024
	ds_read_b128 v[170:173], v174 offset:2048
	ds_read_b128 v[174:177], v174 offset:3072
	ds_read_b128 v[178:181], v186
	ds_read_b128 v[182:185], v186 offset:1024
	ds_read_b128 v[204:207], v186 offset:2048
	ds_read_b128 v[208:211], v186 offset:3072
	v_lshl_add_u64 v[186:187], s[36:37], 0, v[156:157]
	s_add_i32 m0, s54, 0xc000
	ds_read_b128 v[212:215], v169
	ds_read_b128 v[216:219], v169 offset:1024
	ds_read_b128 v[220:223], v169 offset:2048
	ds_read_b128 v[224:227], v169 offset:3072
	ds_read_b128 v[228:231], v169 offset:4096
	ds_read_b128 v[232:235], v169 offset:5120
	ds_read_b128 v[236:239], v169 offset:6144
	ds_read_b128 v[240:243], v169 offset:7168
	global_load_lds_dwordx4 v[186:187], off
	v_lshl_add_u64 v[186:187], s[36:37], 0, v[158:159]
	s_add_i32 m0, s54, 0xe000
	s_nop 0
	global_load_lds_dwordx4 v[186:187], off
	s_waitcnt vmcnt(8)
	s_waitcnt lgkmcnt(0)
	s_barrier
	s_setprio 1
	v_mfma_f32_16x16x32_bf16 v[126:129], v[160:163], v[212:215], v[126:129]
	v_mfma_f32_16x16x32_bf16 v[122:125], v[170:173], v[212:215], v[122:125]
	v_mfma_f32_16x16x32_bf16 v[110:113], v[160:163], v[220:223], v[110:113]
	v_mfma_f32_16x16x32_bf16 v[106:109], v[170:173], v[220:223], v[106:109]
	v_mfma_f32_16x16x32_bf16 v[94:97], v[160:163], v[228:231], v[94:97]
	v_mfma_f32_16x16x32_bf16 v[90:93], v[170:173], v[228:231], v[90:93]
	v_mfma_f32_16x16x32_bf16 v[78:81], v[160:163], v[236:239], v[78:81]
	v_mfma_f32_16x16x32_bf16 v[74:77], v[170:173], v[236:239], v[74:77]
	s_setprio 0
	s_setprio 1
	v_mfma_f32_16x16x32_bf16 v[126:129], v[164:167], v[216:219], v[126:129]
	v_mfma_f32_16x16x32_bf16 v[122:125], v[174:177], v[216:219], v[122:125]
	v_mfma_f32_16x16x32_bf16 v[110:113], v[164:167], v[224:227], v[110:113]
	v_mfma_f32_16x16x32_bf16 v[106:109], v[174:177], v[224:227], v[106:109]
	v_mfma_f32_16x16x32_bf16 v[94:97], v[164:167], v[232:235], v[94:97]
	v_mfma_f32_16x16x32_bf16 v[90:93], v[174:177], v[232:235], v[90:93]
	v_mfma_f32_16x16x32_bf16 v[78:81], v[164:167], v[240:243], v[78:81]
	v_mfma_f32_16x16x32_bf16 v[74:77], v[174:177], v[240:243], v[74:77]
	s_setprio 0
	s_setprio 1
	v_mfma_f32_16x16x32_bf16 v[118:121], v[178:181], v[212:215], v[118:121]
	v_mfma_f32_16x16x32_bf16 v[114:117], v[204:207], v[212:215], v[114:117]
	v_mfma_f32_16x16x32_bf16 v[102:105], v[178:181], v[220:223], v[102:105]
	v_mfma_f32_16x16x32_bf16 v[98:101], v[204:207], v[220:223], v[98:101]
	v_mfma_f32_16x16x32_bf16 v[86:89], v[178:181], v[228:231], v[86:89]
	v_mfma_f32_16x16x32_bf16 v[82:85], v[204:207], v[228:231], v[82:85]
	v_mfma_f32_16x16x32_bf16 v[70:73], v[178:181], v[236:239], v[70:73]
	v_mfma_f32_16x16x32_bf16 v[66:69], v[204:207], v[236:239], v[66:69]
	s_setprio 0
	s_setprio 1
	v_mfma_f32_16x16x32_bf16 v[118:121], v[182:185], v[216:219], v[118:121]
	v_mfma_f32_16x16x32_bf16 v[114:117], v[208:211], v[216:219], v[114:117]
	v_mfma_f32_16x16x32_bf16 v[102:105], v[182:185], v[224:227], v[102:105]
	v_mfma_f32_16x16x32_bf16 v[98:101], v[208:211], v[224:227], v[98:101]
	v_mfma_f32_16x16x32_bf16 v[86:89], v[182:185], v[232:235], v[86:89]
	v_mfma_f32_16x16x32_bf16 v[82:85], v[208:211], v[232:235], v[82:85]
	v_mfma_f32_16x16x32_bf16 v[70:73], v[182:185], v[240:243], v[70:73]
	v_mfma_f32_16x16x32_bf16 v[66:69], v[208:211], v[240:243], v[66:69]
	s_setprio 0
	s_barrier
	s_add_i32 s36, s47, s4
	v_lshl_add_u64 v[186:187], s[18:19], 0, v[148:149]
	s_mov_b32 m0, s36
	ds_read_b128 v[212:215], v169 offset:16384
	ds_read_b128 v[216:219], v169 offset:17408
	ds_read_b128 v[220:223], v169 offset:18432
	ds_read_b128 v[224:227], v169 offset:19456
	ds_read_b128 v[228:231], v169 offset:20480
	ds_read_b128 v[232:235], v169 offset:21504
	ds_read_b128 v[236:239], v169 offset:22528
	ds_read_b128 v[240:243], v169 offset:23552
	global_load_lds_dwordx4 v[186:187], off
	s_add_i32 m0, s36, 0x2000
	s_add_u32 s36, s18, 0x60000
	v_lshl_add_u64 v[244:245], s[18:19], 0, v[144:145]
	s_addc_u32 s37, s19, 0
	s_add_i32 s47, s76, s4
	global_load_lds_dwordx4 v[244:245], off
	v_lshl_add_u64 v[246:247], s[36:37], 0, v[148:149]
	s_mov_b32 m0, s47
	v_lshl_add_u64 v[248:249], s[44:45], 0, v[146:147]
	global_load_lds_dwordx4 v[246:247], off
	v_lshl_add_u64 v[246:247], s[36:37], 0, v[144:145]
	s_add_i32 m0, s47, 0x2000
	s_nop 0
	global_load_lds_dwordx4 v[246:247], off
	v_lshl_add_u64 v[246:247], s[44:45], 0, v[150:151]
	s_mov_b32 m0, s54
	s_nop 0
	global_load_lds_dwordx4 v[246:247], off
	s_mov_b32 m0, s57
	s_nop 0
	global_load_lds_dwordx4 v[248:249], off
	s_waitcnt vmcnt(8)
	s_waitcnt lgkmcnt(0)
	s_barrier
; #define PG8_STAGE(bufoff, gbase, voff) do { _Pragma("unroll") for (int _i = 0; _i < 2; ++_i) \
;         __builtin_amdgcn_global_load_lds((const unsigned*)((const char*)(gbase) + (voff)[_i]), (PG8_LAS unsigned*)(lds + (bufoff) + ldsw + _i * 8192), 16, 0, 0); } while (0)
; #define PG8_LDA(dst, b, h) do { _Pragma("unroll") for (int m = 0; m < 4; ++m) _Pragma("unroll") for (int k = 0; k < 2; ++k) dst[m][k] = *(const PG8_LAS bf16x8*)(lds + PG8_SA(b, h) + aoff + m * 2048 + k * 1024); } while (0)
; #define PG8_LDB(dst, b, h) do { _Pragma("unroll") for (int n = 0; n < 2; ++n) _Pragma("unroll") for (int k = 0; k < 2; ++k) dst[n][k] = *(const PG8_LAS bf16x8*)(lds + PG8_SB(b, h) + boff + n * 2048 + k * 1024); } while (0)
; #define PG8_MMA(ai, bj, At, Bt) do { __builtin_amdgcn_s_setprio(1); _Pragma("unroll") for (int m = 0; m < 4; ++m) _Pragma("unroll") for (int n = 0; n < 2; ++n) _Pragma("unroll") for (int k = 0; k < 2; ++k) \
;         acc[ai][bj][m][n] = __builtin_amdgcn_mfma_f32_16x16x32_bf16(Bt[n][k], At[m][k], acc[ai][bj][m][n], 0, 0, 0); __builtin_amdgcn_s_setprio(0); } while (0)
; #define PG8_WAIT_V(n) asm volatile("s_waitcnt vmcnt(" #n ")" ::: "memory")
; #define PG8_WAIT_L(n) asm volatile("s_waitcnt lgkmcnt(" #n ")" ::: "memory")
; #define PG8_BAR __builtin_amdgcn_s_barrier()
; #define PG8_SCHED __builtin_amdgcn_sched_barrier(0)
; template <class Epi, class Sched, bool ALIGN_EPI = false, bool SP2 = false>
; __device__ __forceinline__ void gemm_phase(PG8_LAS unsigned char* lds, const Gemm g, const Sched& S, const Epi& E) {
;     ...
;             PG8_WAIT_V(8); PG8_WAIT_L(0); PG8_BAR; PG8_MMA(1, 0, At, B0); PG8_MMA(1, 1, At, B1); PG8_BAR; PG8_SCHED;
;             PG8_LDB(B0, 1, 0); PG8_LDB(B1, 1, 1); PG8_SCHED; PG8_LDA(At, 1, 0); PG8_STAGE(PG8_SA(0, 1), a2 + hstep, voffA);
;             PG8_WAIT_V(8); PG8_WAIT_L(0); PG8_BAR; PG8_MMA(0, 0, At, B0); PG8_MMA(0, 1, At, B1); PG8_BAR; PG8_SCHED;
;             PG8_LDA(At, 1, 1); PG8_STAGE(PG8_SB(1, 0), b3, voffB); PG8_STAGE(PG8_SB(1, 1), b3 + hstep, voffB); PG8_STAGE(PG8_SA(1, 0), a3, voffA);
;             PG8_WAIT_V(8); PG8_WAIT_L(0); PG8_BAR; PG8_MMA(1, 0, At, B0); PG8_MMA(1, 1, At, B1); PG8_BAR; PG8_SCHED;
	s_setprio 1
	v_mfma_f32_16x16x32_bf16 v[62:65], v[160:163], v[212:215], v[62:65]
	v_mfma_f32_16x16x32_bf16 v[58:61], v[170:173], v[212:215], v[58:61]
	v_mfma_f32_16x16x32_bf16 v[46:49], v[160:163], v[220:223], v[46:49]
	v_mfma_f32_16x16x32_bf16 v[42:45], v[170:173], v[220:223], v[42:45]
	v_mfma_f32_16x16x32_bf16 v[30:33], v[160:163], v[228:231], v[30:33]
	v_mfma_f32_16x16x32_bf16 v[26:29], v[170:173], v[228:231], v[26:29]
	v_mfma_f32_16x16x32_bf16 v[14:17], v[160:163], v[236:239], v[14:17]
	v_mfma_f32_16x16x32_bf16 v[10:13], v[170:173], v[236:239], v[10:13]
	s_setprio 0
	s_setprio 1
	v_mfma_f32_16x16x32_bf16 v[62:65], v[164:167], v[216:219], v[62:65]
	v_mfma_f32_16x16x32_bf16 v[58:61], v[174:177], v[216:219], v[58:61]
	v_mfma_f32_16x16x32_bf16 v[46:49], v[164:167], v[224:227], v[46:49]
	v_mfma_f32_16x16x32_bf16 v[42:45], v[174:177], v[224:227], v[42:45]
	v_mfma_f32_16x16x32_bf16 v[30:33], v[164:167], v[232:235], v[30:33]
	v_mfma_f32_16x16x32_bf16 v[26:29], v[174:177], v[232:235], v[26:29]
	v_mfma_f32_16x16x32_bf16 v[14:17], v[164:167], v[240:243], v[14:17]
	v_mfma_f32_16x16x32_bf16 v[10:13], v[174:177], v[240:243], v[10:13]
	s_setprio 0
	s_setprio 1
	v_mfma_f32_16x16x32_bf16 v[54:57], v[178:181], v[212:215], v[54:57]
	v_mfma_f32_16x16x32_bf16 v[50:53], v[204:207], v[212:215], v[50:53]
	v_mfma_f32_16x16x32_bf16 v[38:41], v[178:181], v[220:223], v[38:41]
	v_mfma_f32_16x16x32_bf16 v[34:37], v[204:207], v[220:223], v[34:37]
	v_mfma_f32_16x16x32_bf16 v[22:25], v[178:181], v[228:231], v[22:25]
	v_mfma_f32_16x16x32_bf16 v[18:21], v[204:207], v[228:231], v[18:21]
	v_mfma_f32_16x16x32_bf16 v[6:9], v[178:181], v[236:239], v[6:9]
	v_mfma_f32_16x16x32_bf16 v[2:5], v[204:207], v[236:239], v[2:5]
	s_setprio 0
	s_setprio 1
	v_mfma_f32_16x16x32_bf16 v[54:57], v[182:185], v[216:219], v[54:57]
	v_mfma_f32_16x16x32_bf16 v[50:53], v[208:211], v[216:219], v[50:53]
	v_mfma_f32_16x16x32_bf16 v[38:41], v[182:185], v[224:227], v[38:41]
	v_mfma_f32_16x16x32_bf16 v[34:37], v[208:211], v[224:227], v[34:37]
	v_mfma_f32_16x16x32_bf16 v[22:25], v[182:185], v[232:235], v[22:25]
	v_mfma_f32_16x16x32_bf16 v[18:21], v[208:211], v[232:235], v[18:21]
	v_mfma_f32_16x16x32_bf16 v[6:9], v[182:185], v[240:243], v[6:9]
	v_mfma_f32_16x16x32_bf16 v[2:5], v[208:211], v[240:243], v[2:5]
	s_setprio 0
	s_barrier
	s_add_i32 s47, 0, 0x18000
	s_add_i32 s76, 0, 0x1c000
	v_add_u32_e32 v174, s47, v143
	v_add_u32_e32 v203, s76, v143
	ds_read_b128 v[160:163], v174
	ds_read_b128 v[164:167], v174 offset:1024
	ds_read_b128 v[170:173], v174 offset:2048
	ds_read_b128 v[174:177], v174 offset:3072
	ds_read_b128 v[178:181], v203
	ds_read_b128 v[182:185], v203 offset:1024
	ds_read_b128 v[204:207], v203 offset:2048
	ds_read_b128 v[208:211], v203 offset:3072
	s_add_u32 s36, s44, 0x60000
	s_addc_u32 s37, s45, 0
	s_mov_b32 m0, s58
	v_lshl_add_u64 v[250:251], s[36:37], 0, v[150:151]
	ds_read_b128 v[212:215], v169 offset:32768
	ds_read_b128 v[216:219], v169 offset:33792
	ds_read_b128 v[220:223], v169 offset:34816
	ds_read_b128 v[224:227], v169 offset:35840
	ds_read_b128 v[228:231], v169 offset:36864
	ds_read_b128 v[232:235], v169 offset:37888
	ds_read_b128 v[236:239], v169 offset:38912
	ds_read_b128 v[240:243], v169 offset:39936
	global_load_lds_dwordx4 v[250:251], off
	v_lshl_add_u64 v[250:251], s[36:37], 0, v[146:147]
	s_mov_b32 m0, s59
	s_nop 0
	global_load_lds_dwordx4 v[250:251], off
	s_waitcnt vmcnt(8)
	s_waitcnt lgkmcnt(0)
	s_barrier
	s_setprio 1
	v_mfma_f32_16x16x32_bf16 v[126:129], v[160:163], v[212:215], v[126:129]
	v_mfma_f32_16x16x32_bf16 v[122:125], v[170:173], v[212:215], v[122:125]
	v_mfma_f32_16x16x32_bf16 v[110:113], v[160:163], v[220:223], v[110:113]
	v_mfma_f32_16x16x32_bf16 v[106:109], v[170:173], v[220:223], v[106:109]
	v_mfma_f32_16x16x32_bf16 v[94:97], v[160:163], v[228:231], v[94:97]
	v_mfma_f32_16x16x32_bf16 v[90:93], v[170:173], v[228:231], v[90:93]
	v_mfma_f32_16x16x32_bf16 v[78:81], v[160:163], v[236:239], v[78:81]
	v_mfma_f32_16x16x32_bf16 v[74:77], v[170:173], v[236:239], v[74:77]
	s_setprio 0
	s_setprio 1
	v_mfma_f32_16x16x32_bf16 v[126:129], v[164:167], v[216:219], v[126:129]
	v_mfma_f32_16x16x32_bf16 v[122:125], v[174:177], v[216:219], v[122:125]
	v_mfma_f32_16x16x32_bf16 v[110:113], v[164:167], v[224:227], v[110:113]
	v_mfma_f32_16x16x32_bf16 v[106:109], v[174:177], v[224:227], v[106:109]
	v_mfma_f32_16x16x32_bf16 v[94:97], v[164:167], v[232:235], v[94:97]
	v_mfma_f32_16x16x32_bf16 v[90:93], v[174:177], v[232:235], v[90:93]
	v_mfma_f32_16x16x32_bf16 v[78:81], v[164:167], v[240:243], v[78:81]
	v_mfma_f32_16x16x32_bf16 v[74:77], v[174:177], v[240:243], v[74:77]
	s_setprio 0
	s_setprio 1
	v_mfma_f32_16x16x32_bf16 v[118:121], v[178:181], v[212:215], v[118:121]
	v_mfma_f32_16x16x32_bf16 v[114:117], v[204:207], v[212:215], v[114:117]
	v_mfma_f32_16x16x32_bf16 v[102:105], v[178:181], v[220:223], v[102:105]
	v_mfma_f32_16x16x32_bf16 v[98:101], v[204:207], v[220:223], v[98:101]
	v_mfma_f32_16x16x32_bf16 v[86:89], v[178:181], v[228:231], v[86:89]
	v_mfma_f32_16x16x32_bf16 v[82:85], v[204:207], v[228:231], v[82:85]
	v_mfma_f32_16x16x32_bf16 v[70:73], v[178:181], v[236:239], v[70:73]
	v_mfma_f32_16x16x32_bf16 v[66:69], v[204:207], v[236:239], v[66:69]
	s_setprio 0
	s_setprio 1
	v_mfma_f32_16x16x32_bf16 v[118:121], v[182:185], v[216:219], v[118:121]
	v_mfma_f32_16x16x32_bf16 v[114:117], v[208:211], v[216:219], v[114:117]
	v_mfma_f32_16x16x32_bf16 v[102:105], v[182:185], v[224:227], v[102:105]
	v_mfma_f32_16x16x32_bf16 v[98:101], v[208:211], v[224:227], v[98:101]
	v_mfma_f32_16x16x32_bf16 v[86:89], v[182:185], v[232:235], v[86:89]
	v_mfma_f32_16x16x32_bf16 v[82:85], v[208:211], v[232:235], v[82:85]
	v_mfma_f32_16x16x32_bf16 v[70:73], v[182:185], v[240:243], v[70:73]
	v_mfma_f32_16x16x32_bf16 v[66:69], v[208:211], v[240:243], v[66:69]
	s_setprio 0
	s_barrier
; #define PG8_STAGE(bufoff, gbase, voff) do { _Pragma("unroll") for (int _i = 0; _i < 2; ++_i) \
;         __builtin_amdgcn_global_load_lds((const unsigned*)((const char*)(gbase) + (voff)[_i]), (PG8_LAS unsigned*)(lds + (bufoff) + ldsw + _i * 8192), 16, 0, 0); } while (0)
; #define PG8_LDA(dst, b, h) do { _Pragma("unroll") for (int m = 0; m < 4; ++m) _Pragma("unroll") for (int k = 0; k < 2; ++k) dst[m][k] = *(const PG8_LAS bf16x8*)(lds + PG8_SA(b, h) + aoff + m * 2048 + k * 1024); } while (0)
; #define PG8_MMA(ai, bj, At, Bt) do { __builtin_amdgcn_s_setprio(1); _Pragma("unroll") for (int m = 0; m < 4; ++m) _Pragma("unroll") for (int n = 0; n < 2; ++n) _Pragma("unroll") for (int k = 0; k < 2; ++k) \
;         acc[ai][bj][m][n] = __builtin_amdgcn_mfma_f32_16x16x32_bf16(Bt[n][k], At[m][k], acc[ai][bj][m][n], 0, 0, 0); __builtin_amdgcn_s_setprio(0); } while (0)
; #define PG8_WAIT_V(n) asm volatile("s_waitcnt vmcnt(" #n ")" ::: "memory")
; #define PG8_WAIT_L(n) asm volatile("s_waitcnt lgkmcnt(" #n ")" ::: "memory")
; #define PG8_BAR __builtin_amdgcn_s_barrier()
; #define PG8_SCHED __builtin_amdgcn_sched_barrier(0)
; template <class Epi, class Sched, bool ALIGN_EPI = false, bool SP2 = false>
; __device__ __forceinline__ void gemm_phase(PG8_LAS unsigned char* lds, const Gemm g, const Sched& S, const Epi& E) {
;     ...
;         for (int t = 0; t < nt; t += 2) {
;     ...
;             PG8_LDA(At, 1, 1); PG8_STAGE(PG8_SB(1, 0), b3, voffB); PG8_STAGE(PG8_SB(1, 1), b3 + hstep, voffB); PG8_STAGE(PG8_SA(1, 0), a3, voffA);
;             PG8_WAIT_V(8); PG8_WAIT_L(0); PG8_BAR; PG8_MMA(1, 0, At, B0); PG8_MMA(1, 1, At, B1); PG8_BAR; PG8_SCHED;
	s_add_i32 s36, s47, s4
	v_lshl_add_u64 v[186:187], v[186:187], 0, s[68:69]
	s_mov_b32 m0, s36
	ds_read_b128 v[212:215], v169 offset:49152
	ds_read_b128 v[216:219], v169 offset:50176
	ds_read_b128 v[220:223], v169 offset:51200
	ds_read_b128 v[224:227], v169 offset:52224
	ds_read_b128 v[228:231], v169 offset:53248
	ds_read_b128 v[232:235], v169 offset:54272
	ds_read_b128 v[236:239], v169 offset:55296
	ds_read_b128 v[240:243], v169 offset:56320
	global_load_lds_dwordx4 v[186:187], off
	s_add_i32 m0, s36, 0x2000
	s_add_u32 s18, s18, 0x60080
	v_lshl_add_u64 v[186:187], v[244:245], 0, s[68:69]
	s_addc_u32 s19, s19, 0
	s_add_i32 s36, s76, s4
	global_load_lds_dwordx4 v[186:187], off
	v_lshl_add_u64 v[186:187], s[18:19], 0, v[148:149]
	s_mov_b32 m0, s36
	s_nop 0
	global_load_lds_dwordx4 v[186:187], off
	v_lshl_add_u64 v[186:187], s[18:19], 0, v[144:145]
	s_add_i32 m0, s36, 0x2000
	s_nop 0
	global_load_lds_dwordx4 v[186:187], off
	v_lshl_add_u64 v[186:187], v[246:247], 0, s[68:69]
	s_mov_b32 m0, s62
	s_nop 0
	global_load_lds_dwordx4 v[186:187], off
	v_lshl_add_u64 v[186:187], v[248:249], 0, s[68:69]
	s_mov_b32 m0, s63
	s_nop 0
	global_load_lds_dwordx4 v[186:187], off
	s_nop 0
	s_waitcnt vmcnt(8)
	s_waitcnt lgkmcnt(0)
	s_barrier
	s_setprio 1
	v_mfma_f32_16x16x32_bf16 v[62:65], v[160:163], v[212:215], v[62:65]
	v_mfma_f32_16x16x32_bf16 v[58:61], v[170:173], v[212:215], v[58:61]
	v_mfma_f32_16x16x32_bf16 v[46:49], v[160:163], v[220:223], v[46:49]
	v_mfma_f32_16x16x32_bf16 v[42:45], v[170:173], v[220:223], v[42:45]
	v_mfma_f32_16x16x32_bf16 v[30:33], v[160:163], v[228:231], v[30:33]
	v_mfma_f32_16x16x32_bf16 v[26:29], v[170:173], v[228:231], v[26:29]
	v_mfma_f32_16x16x32_bf16 v[14:17], v[160:163], v[236:239], v[14:17]
	v_mfma_f32_16x16x32_bf16 v[10:13], v[170:173], v[236:239], v[10:13]
	s_setprio 0
	s_setprio 1
	v_mfma_f32_16x16x32_bf16 v[62:65], v[164:167], v[216:219], v[62:65]
	v_mfma_f32_16x16x32_bf16 v[58:61], v[174:177], v[216:219], v[58:61]
	v_mfma_f32_16x16x32_bf16 v[46:49], v[164:167], v[224:227], v[46:49]
	v_mfma_f32_16x16x32_bf16 v[42:45], v[174:177], v[224:227], v[42:45]
	v_mfma_f32_16x16x32_bf16 v[30:33], v[164:167], v[232:235], v[30:33]
	v_mfma_f32_16x16x32_bf16 v[26:29], v[174:177], v[232:235], v[26:29]
	v_mfma_f32_16x16x32_bf16 v[14:17], v[164:167], v[240:243], v[14:17]
	v_mfma_f32_16x16x32_bf16 v[10:13], v[174:177], v[240:243], v[10:13]
	s_setprio 0
	s_setprio 1
	v_mfma_f32_16x16x32_bf16 v[54:57], v[178:181], v[212:215], v[54:57]
	v_mfma_f32_16x16x32_bf16 v[50:53], v[204:207], v[212:215], v[50:53]
	v_mfma_f32_16x16x32_bf16 v[38:41], v[178:181], v[220:223], v[38:41]
	v_mfma_f32_16x16x32_bf16 v[34:37], v[204:207], v[220:223], v[34:37]
	v_mfma_f32_16x16x32_bf16 v[22:25], v[178:181], v[228:231], v[22:25]
	v_mfma_f32_16x16x32_bf16 v[18:21], v[204:207], v[228:231], v[18:21]
	v_mfma_f32_16x16x32_bf16 v[6:9], v[178:181], v[236:239], v[6:9]
	v_mfma_f32_16x16x32_bf16 v[2:5], v[204:207], v[236:239], v[2:5]
	s_setprio 0
	s_setprio 1
	v_mfma_f32_16x16x32_bf16 v[54:57], v[182:185], v[216:219], v[54:57]
	v_mfma_f32_16x16x32_bf16 v[50:53], v[208:211], v[216:219], v[50:53]
	v_mfma_f32_16x16x32_bf16 v[38:41], v[182:185], v[224:227], v[38:41]
	v_mfma_f32_16x16x32_bf16 v[34:37], v[208:211], v[224:227], v[34:37]
	v_mfma_f32_16x16x32_bf16 v[22:25], v[182:185], v[232:235], v[22:25]
	v_mfma_f32_16x16x32_bf16 v[18:21], v[208:211], v[232:235], v[18:21]
	v_mfma_f32_16x16x32_bf16 v[6:9], v[182:185], v[240:243], v[6:9]
	v_mfma_f32_16x16x32_bf16 v[2:5], v[208:211], v[240:243], v[2:5]
	s_setprio 0
	s_barrier
	s_add_i32 s46, s46, 2
	s_add_u32 s60, s60, 0x100
	s_addc_u32 s73, s73, 0
	s_cmp_gt_u32 s46, 21
	s_mov_b64 s[36:37], s[42:43]
	s_cbranch_scc0 .LBB0_160
	s_and_b64 vcc, exec, s[10:11]
	s_cbranch_vccz .LBB0_163
	s_barrier

; #define PG8_STAGE(bufoff, gbase, voff) do { _Pragma("unroll") for (int _i = 0; _i < 2; ++_i) \
;         __builtin_amdgcn_global_load_lds((const unsigned*)((const char*)(gbase) + (voff)[_i]), (PG8_LAS unsigned*)(lds + (bufoff) + ldsw + _i * 8192), 16, 0, 0); } while (0)
; #define PG8_LDA(dst, b, h) do { _Pragma("unroll") for (int m = 0; m < 4; ++m) _Pragma("unroll") for (int k = 0; k < 2; ++k) dst[m][k] = *(const PG8_LAS bf16x8*)(lds + PG8_SA(b, h) + aoff + m * 2048 + k * 1024); } while (0)
; #define PG8_LDB(dst, b, h) do { _Pragma("unroll") for (int n = 0; n < 2; ++n) _Pragma("unroll") for (int k = 0; k < 2; ++k) dst[n][k] = *(const PG8_LAS bf16x8*)(lds + PG8_SB(b, h) + boff + n * 2048 + k * 1024); } while (0)
; #define PG8_MMA(ai, bj, At, Bt) do { __builtin_amdgcn_s_setprio(1); _Pragma("unroll") for (int m = 0; m < 4; ++m) _Pragma("unroll") for (int n = 0; n < 2; ++n) _Pragma("unroll") for (int k = 0; k < 2; ++k) \
;         acc[ai][bj][m][n] = __builtin_amdgcn_mfma_f32_16x16x32_bf16(Bt[n][k], At[m][k], acc[ai][bj][m][n], 0, 0, 0); __builtin_amdgcn_s_setprio(0); } while (0)
; #define PG8_WAIT_V(n) asm volatile("s_waitcnt vmcnt(" #n ")" ::: "memory")
; #define PG8_WAIT_L(n) asm volatile("s_waitcnt lgkmcnt(" #n ")" ::: "memory")
; template <class Epi, class Sched, bool ALIGN_EPI = false, bool SP2 = false>
; __device__ __forceinline__ void gemm_phase(PG8_LAS unsigned char* lds, const Gemm g, const Sched& S, const Epi& E) {
;     ...
;             const bool last = (t == nt - 2);
;             const char* a1 = cA + (size_t)(t + 1) * kstep;
;             const char* a2 = last ? nA : cA + (size_t)(t + 2) * kstep; const char* b2 = last ? nB : cB + (size_t)(t + 2) * kstep;
;             const char* a3 = a2 + kstep; const char* b3 = b2 + kstep;
;             if (last && has_next) S.a_ready(nxt);
;             if constexpr (SP2) {
;             PG8_LDB(B0, 0, 0); PG8_LDB(B1, 0, 1); PG8_SCHED; PG8_LDA(At, 0, 0); PG8_STAGE(PG8_SA(1, 1), a1 + hstep, voffA);
;             PG8_WAIT_V(8); PG8_WAIT_L(0); PG8_BAR; PG8_MMA(0, 0, At, B0); PG8_MMA(0, 1, At, B1); PG8_BAR; PG8_SCHED;
;             PG8_LDA(At, 0, 1); PG8_STAGE(PG8_SB(0, 0), b2, voffB); PG8_STAGE(PG8_SB(0, 1), b2 + hstep, voffB); PG8_STAGE(PG8_SA(0, 0), a2, voffA);
;             PG8_WAIT_V(8); PG8_WAIT_L(0); PG8_BAR; PG8_MMA(1, 0, At, B0); PG8_MMA(1, 1, At, B1); PG8_BAR; PG8_SCHED;
.LBB0_281:
	s_add_u32 s18, s36, 0xfff80080
	s_addc_u32 s19, s37, -1
	s_add_i32 s73, 0, 0x10000
	s_cmp_eq_u32 s67, 28
	s_cselect_b32 s43, s9, s19
	s_cselect_b32 s42, s59, s18
	v_add_u32_e32 v163, s73, v160
	s_cselect_b32 s19, s7, s63
	s_cselect_b32 s18, s60, s62
	s_add_i32 s76, 0, 0x14000
	ds_read_b128 v[156:159], v163
	ds_read_b128 v[164:167], v163 offset:1024
	ds_read_b128 v[168:171], v163 offset:2048
	ds_read_b128 v[172:175], v163 offset:3072
	v_add_u32_e32 v163, s76, v160
	ds_read_b128 v[176:179], v163
	ds_read_b128 v[180:183], v163 offset:1024
	ds_read_b128 v[184:187], v163 offset:2048
	ds_read_b128 v[204:207], v163 offset:3072
	v_lshl_add_u64 v[240:241], s[36:37], 0, v[152:153]
	s_add_i32 m0, s30, 0xc000
	ds_read_b128 v[208:211], v162
	ds_read_b128 v[212:215], v162 offset:1024
	ds_read_b128 v[216:219], v162 offset:2048
	ds_read_b128 v[220:223], v162 offset:3072
	ds_read_b128 v[224:227], v162 offset:4096
	ds_read_b128 v[228:231], v162 offset:5120
	ds_read_b128 v[232:235], v162 offset:6144
	ds_read_b128 v[236:239], v162 offset:7168
	global_load_lds_dwordx4 v[240:241], off
	v_lshl_add_u64 v[240:241], s[36:37], 0, v[154:155]
	s_add_i32 m0, s30, 0xe000
	s_nop 0
	global_load_lds_dwordx4 v[240:241], off
	s_waitcnt vmcnt(8)
	s_waitcnt lgkmcnt(0)
	s_barrier
	s_setprio 1
	v_mfma_f32_16x16x32_bf16 v[126:129], v[156:159], v[208:211], v[126:129]
	v_mfma_f32_16x16x32_bf16 v[122:125], v[168:171], v[208:211], v[122:125]
	v_mfma_f32_16x16x32_bf16 v[110:113], v[156:159], v[216:219], v[110:113]
	v_mfma_f32_16x16x32_bf16 v[106:109], v[168:171], v[216:219], v[106:109]
	v_mfma_f32_16x16x32_bf16 v[94:97], v[156:159], v[224:227], v[94:97]
	v_mfma_f32_16x16x32_bf16 v[90:93], v[168:171], v[224:227], v[90:93]
	v_mfma_f32_16x16x32_bf16 v[78:81], v[156:159], v[232:235], v[78:81]
	v_mfma_f32_16x16x32_bf16 v[74:77], v[168:171], v[232:235], v[74:77]
	s_setprio 0
	s_setprio 1
	v_mfma_f32_16x16x32_bf16 v[126:129], v[164:167], v[212:215], v[126:129]
	v_mfma_f32_16x16x32_bf16 v[122:125], v[172:175], v[212:215], v[122:125]
	v_mfma_f32_16x16x32_bf16 v[110:113], v[164:167], v[220:223], v[110:113]
	v_mfma_f32_16x16x32_bf16 v[106:109], v[172:175], v[220:223], v[106:109]
	v_mfma_f32_16x16x32_bf16 v[94:97], v[164:167], v[228:231], v[94:97]
	v_mfma_f32_16x16x32_bf16 v[90:93], v[172:175], v[228:231], v[90:93]
	v_mfma_f32_16x16x32_bf16 v[78:81], v[164:167], v[236:239], v[78:81]
	v_mfma_f32_16x16x32_bf16 v[74:77], v[172:175], v[236:239], v[74:77]
	s_setprio 0
	s_setprio 1
	v_mfma_f32_16x16x32_bf16 v[118:121], v[176:179], v[208:211], v[118:121]
	v_mfma_f32_16x16x32_bf16 v[114:117], v[184:187], v[208:211], v[114:117]
	v_mfma_f32_16x16x32_bf16 v[102:105], v[176:179], v[216:219], v[102:105]
	v_mfma_f32_16x16x32_bf16 v[98:101], v[184:187], v[216:219], v[98:101]
	v_mfma_f32_16x16x32_bf16 v[86:89], v[176:179], v[224:227], v[86:89]
	v_mfma_f32_16x16x32_bf16 v[82:85], v[184:187], v[224:227], v[82:85]
	v_mfma_f32_16x16x32_bf16 v[70:73], v[176:179], v[232:235], v[70:73]
	v_mfma_f32_16x16x32_bf16 v[66:69], v[184:187], v[232:235], v[66:69]
	s_setprio 0
	s_setprio 1
	v_mfma_f32_16x16x32_bf16 v[118:121], v[180:183], v[212:215], v[118:121]
	v_mfma_f32_16x16x32_bf16 v[114:117], v[204:207], v[212:215], v[114:117]
	v_mfma_f32_16x16x32_bf16 v[102:105], v[180:183], v[220:223], v[102:105]
	v_mfma_f32_16x16x32_bf16 v[98:101], v[204:207], v[220:223], v[98:101]
	v_mfma_f32_16x16x32_bf16 v[86:89], v[180:183], v[228:231], v[86:89]
	v_mfma_f32_16x16x32_bf16 v[82:85], v[204:207], v[228:231], v[82:85]
	v_mfma_f32_16x16x32_bf16 v[70:73], v[180:183], v[236:239], v[70:73]
	v_mfma_f32_16x16x32_bf16 v[66:69], v[204:207], v[236:239], v[66:69]
	s_setprio 0
	s_barrier
	s_add_i32 s73, s73, s28
	v_lshl_add_u64 v[240:241], s[18:19], 0, v[146:147]
	s_mov_b32 m0, s73
	ds_read_b128 v[208:211], v162 offset:16384
	ds_read_b128 v[212:215], v162 offset:17408
	ds_read_b128 v[216:219], v162 offset:18432
	ds_read_b128 v[220:223], v162 offset:19456
	ds_read_b128 v[224:227], v162 offset:20480
	ds_read_b128 v[228:231], v162 offset:21504
	ds_read_b128 v[232:235], v162 offset:22528
	ds_read_b128 v[236:239], v162 offset:23552
	global_load_lds_dwordx4 v[240:241], off
	s_add_i32 m0, s73, 0x2000
	s_add_u32 s78, s18, 0x80000
	v_lshl_add_u64 v[242:243], s[18:19], 0, v[142:143]
	s_addc_u32 s79, s19, 0
	s_add_i32 s73, s76, s28
	global_load_lds_dwordx4 v[242:243], off
	v_lshl_add_u64 v[244:245], s[78:79], 0, v[146:147]
	s_mov_b32 m0, s73
	v_lshl_add_u64 v[246:247], s[42:43], 0, v[144:145]
	global_load_lds_dwordx4 v[244:245], off
	v_lshl_add_u64 v[244:245], s[78:79], 0, v[142:143]
	s_add_i32 m0, s73, 0x2000
	s_nop 0
	global_load_lds_dwordx4 v[244:245], off
	v_lshl_add_u64 v[244:245], s[42:43], 0, v[148:149]
	s_mov_b32 m0, s30
	s_nop 0
	global_load_lds_dwordx4 v[244:245], off
	s_mov_b32 m0, s34
	s_nop 0
	global_load_lds_dwordx4 v[246:247], off
	s_waitcnt vmcnt(8)
	s_waitcnt lgkmcnt(0)
	s_barrier
; #define PG8_STAGE(bufoff, gbase, voff) do { _Pragma("unroll") for (int _i = 0; _i < 2; ++_i) \
;         __builtin_amdgcn_global_load_lds((const unsigned*)((const char*)(gbase) + (voff)[_i]), (PG8_LAS unsigned*)(lds + (bufoff) + ldsw + _i * 8192), 16, 0, 0); } while (0)
; #define PG8_LDA(dst, b, h) do { _Pragma("unroll") for (int m = 0; m < 4; ++m) _Pragma("unroll") for (int k = 0; k < 2; ++k) dst[m][k] = *(const PG8_LAS bf16x8*)(lds + PG8_SA(b, h) + aoff + m * 2048 + k * 1024); } while (0)
; #define PG8_LDB(dst, b, h) do { _Pragma("unroll") for (int n = 0; n < 2; ++n) _Pragma("unroll") for (int k = 0; k < 2; ++k) dst[n][k] = *(const PG8_LAS bf16x8*)(lds + PG8_SB(b, h) + boff + n * 2048 + k * 1024); } while (0)
; #define PG8_MMA(ai, bj, At, Bt) do { __builtin_amdgcn_s_setprio(1); _Pragma("unroll") for (int m = 0; m < 4; ++m) _Pragma("unroll") for (int n = 0; n < 2; ++n) _Pragma("unroll") for (int k = 0; k < 2; ++k) \
;         acc[ai][bj][m][n] = __builtin_amdgcn_mfma_f32_16x16x32_bf16(Bt[n][k], At[m][k], acc[ai][bj][m][n], 0, 0, 0); __builtin_amdgcn_s_setprio(0); } while (0)
; #define PG8_WAIT_V(n) asm volatile("s_waitcnt vmcnt(" #n ")" ::: "memory")
; #define PG8_WAIT_L(n) asm volatile("s_waitcnt lgkmcnt(" #n ")" ::: "memory")
; #define PG8_BAR __builtin_amdgcn_s_barrier()
; #define PG8_SCHED __builtin_amdgcn_sched_barrier(0)
; template <class Epi, class Sched, bool ALIGN_EPI = false, bool SP2 = false>
; __device__ __forceinline__ void gemm_phase(PG8_LAS unsigned char* lds, const Gemm g, const Sched& S, const Epi& E) {
;     ...
;             PG8_WAIT_V(8); PG8_WAIT_L(0); PG8_BAR; PG8_MMA(1, 0, At, B0); PG8_MMA(1, 1, At, B1); PG8_BAR; PG8_SCHED;
;             PG8_LDB(B0, 1, 0); PG8_LDB(B1, 1, 1); PG8_SCHED; PG8_LDA(At, 1, 0); PG8_STAGE(PG8_SA(0, 1), a2 + hstep, voffA);
;             PG8_WAIT_V(8); PG8_WAIT_L(0); PG8_BAR; PG8_MMA(0, 0, At, B0); PG8_MMA(0, 1, At, B1); PG8_BAR; PG8_SCHED;
;             PG8_LDA(At, 1, 1); PG8_STAGE(PG8_SB(1, 0), b3, voffB); PG8_STAGE(PG8_SB(1, 1), b3 + hstep, voffB); PG8_STAGE(PG8_SA(1, 0), a3, voffA);
;             PG8_WAIT_V(8); PG8_WAIT_L(0); PG8_BAR; PG8_MMA(1, 0, At, B0); PG8_MMA(1, 1, At, B1); PG8_BAR; PG8_SCHED;
	s_setprio 1
	v_mfma_f32_16x16x32_bf16 v[62:65], v[156:159], v[208:211], v[62:65]
	v_mfma_f32_16x16x32_bf16 v[58:61], v[168:171], v[208:211], v[58:61]
	v_mfma_f32_16x16x32_bf16 v[46:49], v[156:159], v[216:219], v[46:49]
	v_mfma_f32_16x16x32_bf16 v[42:45], v[168:171], v[216:219], v[42:45]
	v_mfma_f32_16x16x32_bf16 v[30:33], v[156:159], v[224:227], v[30:33]
	v_mfma_f32_16x16x32_bf16 v[26:29], v[168:171], v[224:227], v[26:29]
	v_mfma_f32_16x16x32_bf16 v[14:17], v[156:159], v[232:235], v[14:17]
	v_mfma_f32_16x16x32_bf16 v[10:13], v[168:171], v[232:235], v[10:13]
	s_setprio 0
	s_setprio 1
	v_mfma_f32_16x16x32_bf16 v[62:65], v[164:167], v[212:215], v[62:65]
	v_mfma_f32_16x16x32_bf16 v[58:61], v[172:175], v[212:215], v[58:61]
	v_mfma_f32_16x16x32_bf16 v[46:49], v[164:167], v[220:223], v[46:49]
	v_mfma_f32_16x16x32_bf16 v[42:45], v[172:175], v[220:223], v[42:45]
	v_mfma_f32_16x16x32_bf16 v[30:33], v[164:167], v[228:231], v[30:33]
	v_mfma_f32_16x16x32_bf16 v[26:29], v[172:175], v[228:231], v[26:29]
	v_mfma_f32_16x16x32_bf16 v[14:17], v[164:167], v[236:239], v[14:17]
	v_mfma_f32_16x16x32_bf16 v[10:13], v[172:175], v[236:239], v[10:13]
	s_setprio 0
	s_setprio 1
	v_mfma_f32_16x16x32_bf16 v[54:57], v[176:179], v[208:211], v[54:57]
	v_mfma_f32_16x16x32_bf16 v[50:53], v[184:187], v[208:211], v[50:53]
	v_mfma_f32_16x16x32_bf16 v[38:41], v[176:179], v[216:219], v[38:41]
	v_mfma_f32_16x16x32_bf16 v[34:37], v[184:187], v[216:219], v[34:37]
	v_mfma_f32_16x16x32_bf16 v[22:25], v[176:179], v[224:227], v[22:25]
	v_mfma_f32_16x16x32_bf16 v[18:21], v[184:187], v[224:227], v[18:21]
	v_mfma_f32_16x16x32_bf16 v[6:9], v[176:179], v[232:235], v[6:9]
	v_mfma_f32_16x16x32_bf16 v[2:5], v[184:187], v[232:235], v[2:5]
	s_setprio 0
	s_setprio 1
	v_mfma_f32_16x16x32_bf16 v[54:57], v[180:183], v[212:215], v[54:57]
	v_mfma_f32_16x16x32_bf16 v[50:53], v[204:207], v[212:215], v[50:53]
	v_mfma_f32_16x16x32_bf16 v[38:41], v[180:183], v[220:223], v[38:41]
	v_mfma_f32_16x16x32_bf16 v[34:37], v[204:207], v[220:223], v[34:37]
	v_mfma_f32_16x16x32_bf16 v[22:25], v[180:183], v[228:231], v[22:25]
	v_mfma_f32_16x16x32_bf16 v[18:21], v[204:207], v[228:231], v[18:21]
	v_mfma_f32_16x16x32_bf16 v[6:9], v[180:183], v[236:239], v[6:9]
	v_mfma_f32_16x16x32_bf16 v[2:5], v[204:207], v[236:239], v[2:5]
	s_setprio 0
	s_barrier
	s_add_i32 s73, 0, 0x18000
	v_add_u32_e32 v163, s73, v160
	s_add_i32 s76, 0, 0x1c000
	ds_read_b128 v[156:159], v163
	ds_read_b128 v[164:167], v163 offset:1024
	ds_read_b128 v[168:171], v163 offset:2048
	ds_read_b128 v[172:175], v163 offset:3072
	v_add_u32_e32 v163, s76, v160
	ds_read_b128 v[176:179], v163
	ds_read_b128 v[180:183], v163 offset:1024
	ds_read_b128 v[184:187], v163 offset:2048
	ds_read_b128 v[204:207], v163 offset:3072
	s_add_u32 s42, s42, 0x80000
	s_addc_u32 s43, s43, 0
	s_mov_b32 m0, s44
	v_lshl_add_u64 v[248:249], s[42:43], 0, v[148:149]
	ds_read_b128 v[208:211], v162 offset:32768
	ds_read_b128 v[212:215], v162 offset:33792
	ds_read_b128 v[216:219], v162 offset:34816
	ds_read_b128 v[220:223], v162 offset:35840
	ds_read_b128 v[224:227], v162 offset:36864
	ds_read_b128 v[228:231], v162 offset:37888
	ds_read_b128 v[232:235], v162 offset:38912
	ds_read_b128 v[236:239], v162 offset:39936
	global_load_lds_dwordx4 v[248:249], off
	v_lshl_add_u64 v[248:249], s[42:43], 0, v[144:145]
	s_mov_b32 m0, s45
	s_nop 0
	global_load_lds_dwordx4 v[248:249], off
	s_waitcnt vmcnt(8)
	s_waitcnt lgkmcnt(0)
	s_barrier
	s_setprio 1
	v_mfma_f32_16x16x32_bf16 v[126:129], v[156:159], v[208:211], v[126:129]
	v_mfma_f32_16x16x32_bf16 v[122:125], v[168:171], v[208:211], v[122:125]
	v_mfma_f32_16x16x32_bf16 v[110:113], v[156:159], v[216:219], v[110:113]
	v_mfma_f32_16x16x32_bf16 v[106:109], v[168:171], v[216:219], v[106:109]
	v_mfma_f32_16x16x32_bf16 v[94:97], v[156:159], v[224:227], v[94:97]
	v_mfma_f32_16x16x32_bf16 v[90:93], v[168:171], v[224:227], v[90:93]
	v_mfma_f32_16x16x32_bf16 v[78:81], v[156:159], v[232:235], v[78:81]
	v_mfma_f32_16x16x32_bf16 v[74:77], v[168:171], v[232:235], v[74:77]
	s_setprio 0
	s_setprio 1
	v_mfma_f32_16x16x32_bf16 v[126:129], v[164:167], v[212:215], v[126:129]
	v_mfma_f32_16x16x32_bf16 v[122:125], v[172:175], v[212:215], v[122:125]
	v_mfma_f32_16x16x32_bf16 v[110:113], v[164:167], v[220:223], v[110:113]
	v_mfma_f32_16x16x32_bf16 v[106:109], v[172:175], v[220:223], v[106:109]
	v_mfma_f32_16x16x32_bf16 v[94:97], v[164:167], v[228:231], v[94:97]
	v_mfma_f32_16x16x32_bf16 v[90:93], v[172:175], v[228:231], v[90:93]
	v_mfma_f32_16x16x32_bf16 v[78:81], v[164:167], v[236:239], v[78:81]
	v_mfma_f32_16x16x32_bf16 v[74:77], v[172:175], v[236:239], v[74:77]
	s_setprio 0
	s_setprio 1
	v_mfma_f32_16x16x32_bf16 v[118:121], v[176:179], v[208:211], v[118:121]
	v_mfma_f32_16x16x32_bf16 v[114:117], v[184:187], v[208:211], v[114:117]
	v_mfma_f32_16x16x32_bf16 v[102:105], v[176:179], v[216:219], v[102:105]
	v_mfma_f32_16x16x32_bf16 v[98:101], v[184:187], v[216:219], v[98:101]
	v_mfma_f32_16x16x32_bf16 v[86:89], v[176:179], v[224:227], v[86:89]
	v_mfma_f32_16x16x32_bf16 v[82:85], v[184:187], v[224:227], v[82:85]
	v_mfma_f32_16x16x32_bf16 v[70:73], v[176:179], v[232:235], v[70:73]
	v_mfma_f32_16x16x32_bf16 v[66:69], v[184:187], v[232:235], v[66:69]
	s_setprio 0
	s_setprio 1
	v_mfma_f32_16x16x32_bf16 v[118:121], v[180:183], v[212:215], v[118:121]
	v_mfma_f32_16x16x32_bf16 v[114:117], v[204:207], v[212:215], v[114:117]
	v_mfma_f32_16x16x32_bf16 v[102:105], v[180:183], v[220:223], v[102:105]
	v_mfma_f32_16x16x32_bf16 v[98:101], v[204:207], v[220:223], v[98:101]
	v_mfma_f32_16x16x32_bf16 v[86:89], v[180:183], v[228:231], v[86:89]
	v_mfma_f32_16x16x32_bf16 v[82:85], v[204:207], v[228:231], v[82:85]
	v_mfma_f32_16x16x32_bf16 v[70:73], v[180:183], v[236:239], v[70:73]
	v_mfma_f32_16x16x32_bf16 v[66:69], v[204:207], v[236:239], v[66:69]
	s_setprio 0
	s_barrier
; #define PG8_STAGE(bufoff, gbase, voff) do { _Pragma("unroll") for (int _i = 0; _i < 2; ++_i) \
;         __builtin_amdgcn_global_load_lds((const unsigned*)((const char*)(gbase) + (voff)[_i]), (PG8_LAS unsigned*)(lds + (bufoff) + ldsw + _i * 8192), 16, 0, 0); } while (0)
; #define PG8_LDA(dst, b, h) do { _Pragma("unroll") for (int m = 0; m < 4; ++m) _Pragma("unroll") for (int k = 0; k < 2; ++k) dst[m][k] = *(const PG8_LAS bf16x8*)(lds + PG8_SA(b, h) + aoff + m * 2048 + k * 1024); } while (0)
; #define PG8_MMA(ai, bj, At, Bt) do { __builtin_amdgcn_s_setprio(1); _Pragma("unroll") for (int m = 0; m < 4; ++m) _Pragma("unroll") for (int n = 0; n < 2; ++n) _Pragma("unroll") for (int k = 0; k < 2; ++k) \
;         acc[ai][bj][m][n] = __builtin_amdgcn_mfma_f32_16x16x32_bf16(Bt[n][k], At[m][k], acc[ai][bj][m][n], 0, 0, 0); __builtin_amdgcn_s_setprio(0); } while (0)
; #define PG8_WAIT_V(n) asm volatile("s_waitcnt vmcnt(" #n ")" ::: "memory")
; #define PG8_WAIT_L(n) asm volatile("s_waitcnt lgkmcnt(" #n ")" ::: "memory")
; #define PG8_BAR __builtin_amdgcn_s_barrier()
; #define PG8_SCHED __builtin_amdgcn_sched_barrier(0)
;     __device__ __forceinline__ void operator()(const f32x4 (&acc)[2][2][4][2], const Unit& u, int wr, int wc, int fr, int fq) const {
;     ...
;         if (u.pn >= 30) {
; template <class Epi, class Sched, bool ALIGN_EPI = false, bool SP2 = false>
; __device__ __forceinline__ void gemm_phase(PG8_LAS unsigned char* lds, const Gemm g, const Sched& S, const Epi& E) {
;     ...
;             PG8_LDA(At, 1, 1); PG8_STAGE(PG8_SB(1, 0), b3, voffB); PG8_STAGE(PG8_SB(1, 1), b3 + hstep, voffB); PG8_STAGE(PG8_SA(1, 0), a3, voffA);
;             PG8_WAIT_V(8); PG8_WAIT_L(0); PG8_BAR; PG8_MMA(1, 0, At, B0); PG8_MMA(1, 1, At, B1); PG8_BAR; PG8_SCHED;
	s_add_i32 s42, s73, s28
	v_lshl_add_u64 v[240:241], v[240:241], 0, s[68:69]
	s_mov_b32 m0, s42
	ds_read_b128 v[208:211], v162 offset:49152
	ds_read_b128 v[212:215], v162 offset:50176
	ds_read_b128 v[216:219], v162 offset:51200
	ds_read_b128 v[220:223], v162 offset:52224
	ds_read_b128 v[224:227], v162 offset:53248
	ds_read_b128 v[228:231], v162 offset:54272
	ds_read_b128 v[232:235], v162 offset:55296
	ds_read_b128 v[236:239], v162 offset:56320
	global_load_lds_dwordx4 v[240:241], off
	s_add_i32 m0, s42, 0x2000
	s_add_u32 s18, s18, 0x80080
	v_lshl_add_u64 v[240:241], v[242:243], 0, s[68:69]
	s_addc_u32 s19, s19, 0
	s_add_i32 s42, s76, s28
	global_load_lds_dwordx4 v[240:241], off
	v_lshl_add_u64 v[240:241], s[18:19], 0, v[146:147]
	s_mov_b32 m0, s42
	s_nop 0
	global_load_lds_dwordx4 v[240:241], off
	v_lshl_add_u64 v[240:241], s[18:19], 0, v[142:143]
	s_add_i32 m0, s42, 0x2000
	s_nop 0
	global_load_lds_dwordx4 v[240:241], off
	v_lshl_add_u64 v[240:241], v[244:245], 0, s[68:69]
	s_mov_b32 m0, s46
	s_nop 0
	global_load_lds_dwordx4 v[240:241], off
	v_lshl_add_u64 v[240:241], v[246:247], 0, s[68:69]
	s_mov_b32 m0, s47
	s_nop 0
	global_load_lds_dwordx4 v[240:241], off
	s_nop 0
	s_waitcnt vmcnt(8)
	s_waitcnt lgkmcnt(0)
	s_barrier
	s_setprio 1
	v_mfma_f32_16x16x32_bf16 v[62:65], v[156:159], v[208:211], v[62:65]
	v_mfma_f32_16x16x32_bf16 v[58:61], v[168:171], v[208:211], v[58:61]
	v_mfma_f32_16x16x32_bf16 v[46:49], v[156:159], v[216:219], v[46:49]
	v_mfma_f32_16x16x32_bf16 v[42:45], v[168:171], v[216:219], v[42:45]
	v_mfma_f32_16x16x32_bf16 v[30:33], v[156:159], v[224:227], v[30:33]
	v_mfma_f32_16x16x32_bf16 v[26:29], v[168:171], v[224:227], v[26:29]
	v_mfma_f32_16x16x32_bf16 v[14:17], v[156:159], v[232:235], v[14:17]
	v_mfma_f32_16x16x32_bf16 v[10:13], v[168:171], v[232:235], v[10:13]
	s_setprio 0
	s_setprio 1
	v_mfma_f32_16x16x32_bf16 v[62:65], v[164:167], v[212:215], v[62:65]
	v_mfma_f32_16x16x32_bf16 v[58:61], v[172:175], v[212:215], v[58:61]
	v_mfma_f32_16x16x32_bf16 v[46:49], v[164:167], v[220:223], v[46:49]
	v_mfma_f32_16x16x32_bf16 v[42:45], v[172:175], v[220:223], v[42:45]
	v_mfma_f32_16x16x32_bf16 v[30:33], v[164:167], v[228:231], v[30:33]
	v_mfma_f32_16x16x32_bf16 v[26:29], v[172:175], v[228:231], v[26:29]
	v_mfma_f32_16x16x32_bf16 v[14:17], v[164:167], v[236:239], v[14:17]
	v_mfma_f32_16x16x32_bf16 v[10:13], v[172:175], v[236:239], v[10:13]
	s_setprio 0
	s_setprio 1
	v_mfma_f32_16x16x32_bf16 v[54:57], v[176:179], v[208:211], v[54:57]
	v_mfma_f32_16x16x32_bf16 v[50:53], v[184:187], v[208:211], v[50:53]
	v_mfma_f32_16x16x32_bf16 v[38:41], v[176:179], v[216:219], v[38:41]
	v_mfma_f32_16x16x32_bf16 v[34:37], v[184:187], v[216:219], v[34:37]
	v_mfma_f32_16x16x32_bf16 v[22:25], v[176:179], v[224:227], v[22:25]
	v_mfma_f32_16x16x32_bf16 v[18:21], v[184:187], v[224:227], v[18:21]
	v_mfma_f32_16x16x32_bf16 v[6:9], v[176:179], v[232:235], v[6:9]
	v_mfma_f32_16x16x32_bf16 v[2:5], v[184:187], v[232:235], v[2:5]
	s_setprio 0
	s_setprio 1
	v_mfma_f32_16x16x32_bf16 v[54:57], v[180:183], v[212:215], v[54:57]
	v_mfma_f32_16x16x32_bf16 v[50:53], v[204:207], v[212:215], v[50:53]
	v_mfma_f32_16x16x32_bf16 v[38:41], v[180:183], v[220:223], v[38:41]
	v_mfma_f32_16x16x32_bf16 v[34:37], v[204:207], v[220:223], v[34:37]
	v_mfma_f32_16x16x32_bf16 v[22:25], v[180:183], v[228:231], v[22:25]
	v_mfma_f32_16x16x32_bf16 v[18:21], v[204:207], v[228:231], v[18:21]
	v_mfma_f32_16x16x32_bf16 v[6:9], v[180:183], v[236:239], v[6:9]
	v_mfma_f32_16x16x32_bf16 v[2:5], v[204:207], v[236:239], v[2:5]
	s_setprio 0
	s_barrier
	s_add_i32 s67, s67, 2
	s_add_u32 s36, s36, 0x100
	s_addc_u32 s37, s37, 0
	s_add_u32 s62, s62, 0x100
	s_addc_u32 s63, s63, 0
	s_cmp_gt_u32 s67, 29
	s_cbranch_scc0 .LBB0_281
	s_and_b64 vcc, exec, s[4:5]
	s_cbranch_vccnz .LBB0_286
	s_cmp_lt_i32 s57, 30
	s_mov_b64 s[18:19], -1
	s_cbranch_scc1 .LBB0_287
